# v67 + EpiProj (in-proj epilogue) hand-written straight-line fast paths per column-tile kind: plain, silu, rope (wave-uniform skip of non-rotary waves, cos/sin prefetched 4 steps ahead)
# speedup vs baseline: 1.0078x; 1.0078x over previous
.LBB0_268:
	s_ashr_i32 s51, s16, 2
	s_cmp_gt_u32 s51, 5
	s_cbranch_scc1 .Lep_generic
	s_lshl_b32 s61, s60, 8
	s_add_i32 s61, s61, s75
	v_or_b32_e32 v180, s61, v147
	s_cmp_eq_u32 s51, 1
	s_cbranch_scc1 .Lep_kind1
	s_cmp_eq_u32 s51, 4
	s_cbranch_scc1 .Lep_kind4
	v_lshl_or_b32 v181, s16, 8, v146
	v_lshlrev_b32_e32 v181, 1, v181
	v_mad_u32_u24 v181, v180, s87, v181
	s_cmp_eq_u32 s51, 3
	s_cbranch_scc1 .Lep_kind3
	s_cmp_eq_u32 s51, 0
	s_cbranch_scc0 .Lep_silu
	s_mov_b64 s[62:63], s[12:13]
	v_mul_f32_e32 v124, v170, v124
	v_mul_f32_e32 v125, v170, v125
	v_mul_f32_e32 v126, v170, v126
	v_mul_f32_e32 v127, v170, v127
	v_mul_f32_e32 v120, v170, v120
	v_mul_f32_e32 v121, v170, v121
	v_mul_f32_e32 v122, v170, v122
	v_mul_f32_e32 v123, v170, v123
	v_cvt_pk_bf16_f32 v184, v124, v125
	v_cvt_pk_bf16_f32 v185, v126, v127
	v_cvt_pk_bf16_f32 v186, v120, v121
	v_cvt_pk_bf16_f32 v187, v122, v123
	global_store_dwordx4 v181, v[184:187], s[62:63] offset:0
	v_mul_f32_e32 v116, v170, v116
	v_mul_f32_e32 v117, v170, v117
	v_mul_f32_e32 v118, v170, v118
	v_mul_f32_e32 v119, v170, v119
	v_mul_f32_e32 v112, v170, v112
	v_mul_f32_e32 v113, v170, v113
	v_mul_f32_e32 v114, v170, v114
	v_mul_f32_e32 v115, v170, v115
	v_cvt_pk_bf16_f32 v188, v116, v117
	v_cvt_pk_bf16_f32 v189, v118, v119
	v_cvt_pk_bf16_f32 v190, v112, v113
	v_cvt_pk_bf16_f32 v191, v114, v115
	global_store_dwordx4 v181, v[188:191], s[62:63] offset:256
	s_add_u32 s62, s12, 0x30000
	s_addc_u32 s63, s13, 0
	v_mul_f32_e32 v108, v170, v108
	v_mul_f32_e32 v109, v170, v109
	v_mul_f32_e32 v110, v170, v110
	v_mul_f32_e32 v111, v170, v111
	v_mul_f32_e32 v104, v170, v104
	v_mul_f32_e32 v105, v170, v105
	v_mul_f32_e32 v106, v170, v106
	v_mul_f32_e32 v107, v170, v107
	v_cvt_pk_bf16_f32 v184, v108, v109
	v_cvt_pk_bf16_f32 v185, v110, v111
	v_cvt_pk_bf16_f32 v186, v104, v105
	v_cvt_pk_bf16_f32 v187, v106, v107
	global_store_dwordx4 v181, v[184:187], s[62:63] offset:0
	v_mul_f32_e32 v100, v170, v100
	v_mul_f32_e32 v101, v170, v101
	v_mul_f32_e32 v102, v170, v102
	v_mul_f32_e32 v103, v170, v103
	v_mul_f32_e32 v96, v170, v96
	v_mul_f32_e32 v97, v170, v97
	v_mul_f32_e32 v98, v170, v98
	v_mul_f32_e32 v99, v170, v99
	v_cvt_pk_bf16_f32 v188, v100, v101
	v_cvt_pk_bf16_f32 v189, v102, v103
	v_cvt_pk_bf16_f32 v190, v96, v97
	v_cvt_pk_bf16_f32 v191, v98, v99
	global_store_dwordx4 v181, v[188:191], s[62:63] offset:256
	s_add_u32 s62, s12, 0x60000
	s_addc_u32 s63, s13, 0
	v_mul_f32_e32 v92, v170, v92
	v_mul_f32_e32 v93, v170, v93
	v_mul_f32_e32 v94, v170, v94
	v_mul_f32_e32 v95, v170, v95
	v_mul_f32_e32 v88, v170, v88
	v_mul_f32_e32 v89, v170, v89
	v_mul_f32_e32 v90, v170, v90
	v_mul_f32_e32 v91, v170, v91
	v_cvt_pk_bf16_f32 v184, v92, v93
	v_cvt_pk_bf16_f32 v185, v94, v95
	v_cvt_pk_bf16_f32 v186, v88, v89
	v_cvt_pk_bf16_f32 v187, v90, v91
	global_store_dwordx4 v181, v[184:187], s[62:63] offset:0
	v_mul_f32_e32 v84, v170, v84
	v_mul_f32_e32 v85, v170, v85
	v_mul_f32_e32 v86, v170, v86
	v_mul_f32_e32 v87, v170, v87
	v_mul_f32_e32 v80, v170, v80
	v_mul_f32_e32 v81, v170, v81
	v_mul_f32_e32 v82, v170, v82
	v_mul_f32_e32 v83, v170, v83
	v_cvt_pk_bf16_f32 v188, v84, v85
	v_cvt_pk_bf16_f32 v189, v86, v87
	v_cvt_pk_bf16_f32 v190, v80, v81
	v_cvt_pk_bf16_f32 v191, v82, v83
	global_store_dwordx4 v181, v[188:191], s[62:63] offset:256
	s_add_u32 s62, s12, 0x90000
	s_addc_u32 s63, s13, 0
	v_mul_f32_e32 v76, v170, v76
	v_mul_f32_e32 v77, v170, v77
	v_mul_f32_e32 v78, v170, v78
	v_mul_f32_e32 v79, v170, v79
	v_mul_f32_e32 v72, v170, v72
	v_mul_f32_e32 v73, v170, v73
	v_mul_f32_e32 v74, v170, v74
	v_mul_f32_e32 v75, v170, v75
	v_cvt_pk_bf16_f32 v184, v76, v77
	v_cvt_pk_bf16_f32 v185, v78, v79
	v_cvt_pk_bf16_f32 v186, v72, v73
	v_cvt_pk_bf16_f32 v187, v74, v75
	global_store_dwordx4 v181, v[184:187], s[62:63] offset:0
	v_mul_f32_e32 v68, v170, v68
	v_mul_f32_e32 v69, v170, v69
	v_mul_f32_e32 v70, v170, v70
	v_mul_f32_e32 v71, v170, v71
	v_mul_f32_e32 v64, v170, v64
	v_mul_f32_e32 v65, v170, v65
	v_mul_f32_e32 v66, v170, v66
	v_mul_f32_e32 v67, v170, v67
	v_cvt_pk_bf16_f32 v188, v68, v69
	v_cvt_pk_bf16_f32 v189, v70, v71
	v_cvt_pk_bf16_f32 v190, v64, v65
	v_cvt_pk_bf16_f32 v191, v66, v67
	global_store_dwordx4 v181, v[188:191], s[62:63] offset:256
	s_add_u32 s62, s12, 0x180000
	s_addc_u32 s63, s13, 0
	v_mul_f32_e32 v60, v170, v60
	v_mul_f32_e32 v61, v170, v61
	v_mul_f32_e32 v62, v170, v62
	v_mul_f32_e32 v63, v170, v63
	v_mul_f32_e32 v56, v170, v56
	v_mul_f32_e32 v57, v170, v57
	v_mul_f32_e32 v58, v170, v58
	v_mul_f32_e32 v59, v170, v59
	v_cvt_pk_bf16_f32 v184, v60, v61
	v_cvt_pk_bf16_f32 v185, v62, v63
	v_cvt_pk_bf16_f32 v186, v56, v57
	v_cvt_pk_bf16_f32 v187, v58, v59
	global_store_dwordx4 v181, v[184:187], s[62:63] offset:0
	v_mul_f32_e32 v52, v170, v52
	v_mul_f32_e32 v53, v170, v53
	v_mul_f32_e32 v54, v170, v54
	v_mul_f32_e32 v55, v170, v55
	v_mul_f32_e32 v48, v170, v48
	v_mul_f32_e32 v49, v170, v49
	v_mul_f32_e32 v50, v170, v50
	v_mul_f32_e32 v51, v170, v51
	v_cvt_pk_bf16_f32 v188, v52, v53
	v_cvt_pk_bf16_f32 v189, v54, v55
	v_cvt_pk_bf16_f32 v190, v48, v49
	v_cvt_pk_bf16_f32 v191, v50, v51
	global_store_dwordx4 v181, v[188:191], s[62:63] offset:256
	s_add_u32 s62, s12, 0x1b0000
	s_addc_u32 s63, s13, 0
	v_mul_f32_e32 v44, v170, v44
	v_mul_f32_e32 v45, v170, v45
	v_mul_f32_e32 v46, v170, v46
	v_mul_f32_e32 v47, v170, v47
	v_mul_f32_e32 v40, v170, v40
	v_mul_f32_e32 v41, v170, v41
	v_mul_f32_e32 v42, v170, v42
	v_mul_f32_e32 v43, v170, v43
	v_cvt_pk_bf16_f32 v184, v44, v45
	v_cvt_pk_bf16_f32 v185, v46, v47
	v_cvt_pk_bf16_f32 v186, v40, v41
	v_cvt_pk_bf16_f32 v187, v42, v43
	global_store_dwordx4 v181, v[184:187], s[62:63] offset:0
	v_mul_f32_e32 v36, v170, v36
	v_mul_f32_e32 v37, v170, v37
	v_mul_f32_e32 v38, v170, v38
	v_mul_f32_e32 v39, v170, v39
	v_mul_f32_e32 v32, v170, v32
	v_mul_f32_e32 v33, v170, v33
	v_mul_f32_e32 v34, v170, v34
	v_mul_f32_e32 v35, v170, v35
	v_cvt_pk_bf16_f32 v188, v36, v37
	v_cvt_pk_bf16_f32 v189, v38, v39
	v_cvt_pk_bf16_f32 v190, v32, v33
	v_cvt_pk_bf16_f32 v191, v34, v35
	global_store_dwordx4 v181, v[188:191], s[62:63] offset:256
	s_add_u32 s62, s12, 0x1e0000
	s_addc_u32 s63, s13, 0
	v_mul_f32_e32 v28, v170, v28
	v_mul_f32_e32 v29, v170, v29
	v_mul_f32_e32 v30, v170, v30
	v_mul_f32_e32 v31, v170, v31
	v_mul_f32_e32 v24, v170, v24
	v_mul_f32_e32 v25, v170, v25
	v_mul_f32_e32 v26, v170, v26
	v_mul_f32_e32 v27, v170, v27
	v_cvt_pk_bf16_f32 v184, v28, v29
	v_cvt_pk_bf16_f32 v185, v30, v31
	v_cvt_pk_bf16_f32 v186, v24, v25
	v_cvt_pk_bf16_f32 v187, v26, v27
	global_store_dwordx4 v181, v[184:187], s[62:63] offset:0
	v_mul_f32_e32 v20, v170, v20
	v_mul_f32_e32 v21, v170, v21
	v_mul_f32_e32 v22, v170, v22
	v_mul_f32_e32 v23, v170, v23
	v_mul_f32_e32 v16, v170, v16
	v_mul_f32_e32 v17, v170, v17
	v_mul_f32_e32 v18, v170, v18
	v_mul_f32_e32 v19, v170, v19
	v_cvt_pk_bf16_f32 v188, v20, v21
	v_cvt_pk_bf16_f32 v189, v22, v23
	v_cvt_pk_bf16_f32 v190, v16, v17
	v_cvt_pk_bf16_f32 v191, v18, v19
	global_store_dwordx4 v181, v[188:191], s[62:63] offset:256
	s_add_u32 s62, s12, 0x210000
	s_addc_u32 s63, s13, 0
	v_mul_f32_e32 v12, v170, v12
	v_mul_f32_e32 v13, v170, v13
	v_mul_f32_e32 v14, v170, v14
	v_mul_f32_e32 v15, v170, v15
	v_mul_f32_e32 v8, v170, v8
	v_mul_f32_e32 v9, v170, v9
	v_mul_f32_e32 v10, v170, v10
	v_mul_f32_e32 v11, v170, v11
	v_cvt_pk_bf16_f32 v184, v12, v13
	v_cvt_pk_bf16_f32 v185, v14, v15
	v_cvt_pk_bf16_f32 v186, v8, v9
	v_cvt_pk_bf16_f32 v187, v10, v11
	global_store_dwordx4 v181, v[184:187], s[62:63] offset:0
	v_mul_f32_e32 v4, v170, v4
	v_mul_f32_e32 v5, v170, v5
	v_mul_f32_e32 v6, v170, v6
	v_mul_f32_e32 v7, v170, v7
	v_mul_f32_e32 v0, v170, v0
	v_mul_f32_e32 v1, v170, v1
	v_mul_f32_e32 v2, v170, v2
	v_mul_f32_e32 v3, v170, v3
	v_cvt_pk_bf16_f32 v188, v4, v5
	v_cvt_pk_bf16_f32 v189, v6, v7
	v_cvt_pk_bf16_f32 v190, v0, v1
	v_cvt_pk_bf16_f32 v191, v2, v3
	global_store_dwordx4 v181, v[188:191], s[62:63] offset:256
	s_branch .Lep_fast_done
.Lep_silu:
	s_mov_b64 s[62:63], s[12:13]
	v_mul_f32_e32 v192, 0xbfb8aa3b, v124
	v_mul_f32_e32 v193, 0xbfb8aa3b, v125
	v_mul_f32_e32 v194, 0xbfb8aa3b, v126
	v_mul_f32_e32 v195, 0xbfb8aa3b, v127
	v_mul_f32_e32 v196, 0xbfb8aa3b, v120
	v_mul_f32_e32 v197, 0xbfb8aa3b, v121
	v_mul_f32_e32 v198, 0xbfb8aa3b, v122
	v_mul_f32_e32 v199, 0xbfb8aa3b, v123
	v_exp_f32_e32 v192, v192
	v_exp_f32_e32 v193, v193
	v_exp_f32_e32 v194, v194
	v_exp_f32_e32 v195, v195
	v_exp_f32_e32 v196, v196
	v_exp_f32_e32 v197, v197
	v_exp_f32_e32 v198, v198
	v_exp_f32_e32 v199, v199
	v_add_f32_e32 v192, 1.0, v192
	v_add_f32_e32 v193, 1.0, v193
	v_add_f32_e32 v194, 1.0, v194
	v_add_f32_e32 v195, 1.0, v195
	v_add_f32_e32 v196, 1.0, v196
	v_add_f32_e32 v197, 1.0, v197
	v_add_f32_e32 v198, 1.0, v198
	v_add_f32_e32 v199, 1.0, v199
	v_rcp_f32_e32 v192, v192
	v_rcp_f32_e32 v193, v193
	v_rcp_f32_e32 v194, v194
	v_rcp_f32_e32 v195, v195
	v_rcp_f32_e32 v196, v196
	v_rcp_f32_e32 v197, v197
	v_rcp_f32_e32 v198, v198
	v_rcp_f32_e32 v199, v199
	v_mul_f32_e32 v124, v124, v192
	v_mul_f32_e32 v125, v125, v193
	v_mul_f32_e32 v126, v126, v194
	v_mul_f32_e32 v127, v127, v195
	v_mul_f32_e32 v120, v120, v196
	v_mul_f32_e32 v121, v121, v197
	v_mul_f32_e32 v122, v122, v198
	v_mul_f32_e32 v123, v123, v199
	v_cvt_pk_bf16_f32 v184, v124, v125
	v_cvt_pk_bf16_f32 v185, v126, v127
	v_cvt_pk_bf16_f32 v186, v120, v121
	v_cvt_pk_bf16_f32 v187, v122, v123
	global_store_dwordx4 v181, v[184:187], s[62:63] offset:0
	v_mul_f32_e32 v192, 0xbfb8aa3b, v116
	v_mul_f32_e32 v193, 0xbfb8aa3b, v117
	v_mul_f32_e32 v194, 0xbfb8aa3b, v118
	v_mul_f32_e32 v195, 0xbfb8aa3b, v119
	v_mul_f32_e32 v196, 0xbfb8aa3b, v112
	v_mul_f32_e32 v197, 0xbfb8aa3b, v113
	v_mul_f32_e32 v198, 0xbfb8aa3b, v114
	v_mul_f32_e32 v199, 0xbfb8aa3b, v115
	v_exp_f32_e32 v192, v192
	v_exp_f32_e32 v193, v193
	v_exp_f32_e32 v194, v194
	v_exp_f32_e32 v195, v195
	v_exp_f32_e32 v196, v196
	v_exp_f32_e32 v197, v197
	v_exp_f32_e32 v198, v198
	v_exp_f32_e32 v199, v199
	v_add_f32_e32 v192, 1.0, v192
	v_add_f32_e32 v193, 1.0, v193
	v_add_f32_e32 v194, 1.0, v194
	v_add_f32_e32 v195, 1.0, v195
	v_add_f32_e32 v196, 1.0, v196
	v_add_f32_e32 v197, 1.0, v197
	v_add_f32_e32 v198, 1.0, v198
	v_add_f32_e32 v199, 1.0, v199
	v_rcp_f32_e32 v192, v192
	v_rcp_f32_e32 v193, v193
	v_rcp_f32_e32 v194, v194
	v_rcp_f32_e32 v195, v195
	v_rcp_f32_e32 v196, v196
	v_rcp_f32_e32 v197, v197
	v_rcp_f32_e32 v198, v198
	v_rcp_f32_e32 v199, v199
	v_mul_f32_e32 v116, v116, v192
	v_mul_f32_e32 v117, v117, v193
	v_mul_f32_e32 v118, v118, v194
	v_mul_f32_e32 v119, v119, v195
	v_mul_f32_e32 v112, v112, v196
	v_mul_f32_e32 v113, v113, v197
	v_mul_f32_e32 v114, v114, v198
	v_mul_f32_e32 v115, v115, v199
	v_cvt_pk_bf16_f32 v188, v116, v117
	v_cvt_pk_bf16_f32 v189, v118, v119
	v_cvt_pk_bf16_f32 v190, v112, v113
	v_cvt_pk_bf16_f32 v191, v114, v115
	global_store_dwordx4 v181, v[188:191], s[62:63] offset:256
	s_add_u32 s62, s12, 0x30000
	s_addc_u32 s63, s13, 0
	v_mul_f32_e32 v192, 0xbfb8aa3b, v108
	v_mul_f32_e32 v193, 0xbfb8aa3b, v109
	v_mul_f32_e32 v194, 0xbfb8aa3b, v110
	v_mul_f32_e32 v195, 0xbfb8aa3b, v111
	v_mul_f32_e32 v196, 0xbfb8aa3b, v104
	v_mul_f32_e32 v197, 0xbfb8aa3b, v105
	v_mul_f32_e32 v198, 0xbfb8aa3b, v106
	v_mul_f32_e32 v199, 0xbfb8aa3b, v107
	v_exp_f32_e32 v192, v192
	v_exp_f32_e32 v193, v193
	v_exp_f32_e32 v194, v194
	v_exp_f32_e32 v195, v195
	v_exp_f32_e32 v196, v196
	v_exp_f32_e32 v197, v197
	v_exp_f32_e32 v198, v198
	v_exp_f32_e32 v199, v199
	v_add_f32_e32 v192, 1.0, v192
	v_add_f32_e32 v193, 1.0, v193
	v_add_f32_e32 v194, 1.0, v194
	v_add_f32_e32 v195, 1.0, v195
	v_add_f32_e32 v196, 1.0, v196
	v_add_f32_e32 v197, 1.0, v197
	v_add_f32_e32 v198, 1.0, v198
	v_add_f32_e32 v199, 1.0, v199
	v_rcp_f32_e32 v192, v192
	v_rcp_f32_e32 v193, v193
	v_rcp_f32_e32 v194, v194
	v_rcp_f32_e32 v195, v195
	v_rcp_f32_e32 v196, v196
	v_rcp_f32_e32 v197, v197
	v_rcp_f32_e32 v198, v198
	v_rcp_f32_e32 v199, v199
	v_mul_f32_e32 v108, v108, v192
	v_mul_f32_e32 v109, v109, v193
	v_mul_f32_e32 v110, v110, v194
	v_mul_f32_e32 v111, v111, v195
	v_mul_f32_e32 v104, v104, v196
	v_mul_f32_e32 v105, v105, v197
	v_mul_f32_e32 v106, v106, v198
	v_mul_f32_e32 v107, v107, v199
	v_cvt_pk_bf16_f32 v184, v108, v109
	v_cvt_pk_bf16_f32 v185, v110, v111
	v_cvt_pk_bf16_f32 v186, v104, v105
	v_cvt_pk_bf16_f32 v187, v106, v107
	global_store_dwordx4 v181, v[184:187], s[62:63] offset:0
	v_mul_f32_e32 v192, 0xbfb8aa3b, v100
	v_mul_f32_e32 v193, 0xbfb8aa3b, v101
	v_mul_f32_e32 v194, 0xbfb8aa3b, v102
	v_mul_f32_e32 v195, 0xbfb8aa3b, v103
	v_mul_f32_e32 v196, 0xbfb8aa3b, v96
	v_mul_f32_e32 v197, 0xbfb8aa3b, v97
	v_mul_f32_e32 v198, 0xbfb8aa3b, v98
	v_mul_f32_e32 v199, 0xbfb8aa3b, v99
	v_exp_f32_e32 v192, v192
	v_exp_f32_e32 v193, v193
	v_exp_f32_e32 v194, v194
	v_exp_f32_e32 v195, v195
	v_exp_f32_e32 v196, v196
	v_exp_f32_e32 v197, v197
	v_exp_f32_e32 v198, v198
	v_exp_f32_e32 v199, v199
	v_add_f32_e32 v192, 1.0, v192
	v_add_f32_e32 v193, 1.0, v193
	v_add_f32_e32 v194, 1.0, v194
	v_add_f32_e32 v195, 1.0, v195
	v_add_f32_e32 v196, 1.0, v196
	v_add_f32_e32 v197, 1.0, v197
	v_add_f32_e32 v198, 1.0, v198
	v_add_f32_e32 v199, 1.0, v199
	v_rcp_f32_e32 v192, v192
	v_rcp_f32_e32 v193, v193
	v_rcp_f32_e32 v194, v194
	v_rcp_f32_e32 v195, v195
	v_rcp_f32_e32 v196, v196
	v_rcp_f32_e32 v197, v197
	v_rcp_f32_e32 v198, v198
	v_rcp_f32_e32 v199, v199
	v_mul_f32_e32 v100, v100, v192
	v_mul_f32_e32 v101, v101, v193
	v_mul_f32_e32 v102, v102, v194
	v_mul_f32_e32 v103, v103, v195
	v_mul_f32_e32 v96, v96, v196
	v_mul_f32_e32 v97, v97, v197
	v_mul_f32_e32 v98, v98, v198
	v_mul_f32_e32 v99, v99, v199
	v_cvt_pk_bf16_f32 v188, v100, v101
	v_cvt_pk_bf16_f32 v189, v102, v103
	v_cvt_pk_bf16_f32 v190, v96, v97
	v_cvt_pk_bf16_f32 v191, v98, v99
	global_store_dwordx4 v181, v[188:191], s[62:63] offset:256
	s_add_u32 s62, s12, 0x60000
	s_addc_u32 s63, s13, 0
	v_mul_f32_e32 v192, 0xbfb8aa3b, v92
	v_mul_f32_e32 v193, 0xbfb8aa3b, v93
	v_mul_f32_e32 v194, 0xbfb8aa3b, v94
	v_mul_f32_e32 v195, 0xbfb8aa3b, v95
	v_mul_f32_e32 v196, 0xbfb8aa3b, v88
	v_mul_f32_e32 v197, 0xbfb8aa3b, v89
	v_mul_f32_e32 v198, 0xbfb8aa3b, v90
	v_mul_f32_e32 v199, 0xbfb8aa3b, v91
	v_exp_f32_e32 v192, v192
	v_exp_f32_e32 v193, v193
	v_exp_f32_e32 v194, v194
	v_exp_f32_e32 v195, v195
	v_exp_f32_e32 v196, v196
	v_exp_f32_e32 v197, v197
	v_exp_f32_e32 v198, v198
	v_exp_f32_e32 v199, v199
	v_add_f32_e32 v192, 1.0, v192
	v_add_f32_e32 v193, 1.0, v193
	v_add_f32_e32 v194, 1.0, v194
	v_add_f32_e32 v195, 1.0, v195
	v_add_f32_e32 v196, 1.0, v196
	v_add_f32_e32 v197, 1.0, v197
	v_add_f32_e32 v198, 1.0, v198
	v_add_f32_e32 v199, 1.0, v199
	v_rcp_f32_e32 v192, v192
	v_rcp_f32_e32 v193, v193
	v_rcp_f32_e32 v194, v194
	v_rcp_f32_e32 v195, v195
	v_rcp_f32_e32 v196, v196
	v_rcp_f32_e32 v197, v197
	v_rcp_f32_e32 v198, v198
	v_rcp_f32_e32 v199, v199
	v_mul_f32_e32 v92, v92, v192
	v_mul_f32_e32 v93, v93, v193
	v_mul_f32_e32 v94, v94, v194
	v_mul_f32_e32 v95, v95, v195
	v_mul_f32_e32 v88, v88, v196
	v_mul_f32_e32 v89, v89, v197
	v_mul_f32_e32 v90, v90, v198
	v_mul_f32_e32 v91, v91, v199
	v_cvt_pk_bf16_f32 v184, v92, v93
	v_cvt_pk_bf16_f32 v185, v94, v95
	v_cvt_pk_bf16_f32 v186, v88, v89
	v_cvt_pk_bf16_f32 v187, v90, v91
	global_store_dwordx4 v181, v[184:187], s[62:63] offset:0
	v_mul_f32_e32 v192, 0xbfb8aa3b, v84
	v_mul_f32_e32 v193, 0xbfb8aa3b, v85
	v_mul_f32_e32 v194, 0xbfb8aa3b, v86
	v_mul_f32_e32 v195, 0xbfb8aa3b, v87
	v_mul_f32_e32 v196, 0xbfb8aa3b, v80
	v_mul_f32_e32 v197, 0xbfb8aa3b, v81
	v_mul_f32_e32 v198, 0xbfb8aa3b, v82
	v_mul_f32_e32 v199, 0xbfb8aa3b, v83
	v_exp_f32_e32 v192, v192
	v_exp_f32_e32 v193, v193
	v_exp_f32_e32 v194, v194
	v_exp_f32_e32 v195, v195
	v_exp_f32_e32 v196, v196
	v_exp_f32_e32 v197, v197
	v_exp_f32_e32 v198, v198
	v_exp_f32_e32 v199, v199
	v_add_f32_e32 v192, 1.0, v192
	v_add_f32_e32 v193, 1.0, v193
	v_add_f32_e32 v194, 1.0, v194
	v_add_f32_e32 v195, 1.0, v195
	v_add_f32_e32 v196, 1.0, v196
	v_add_f32_e32 v197, 1.0, v197
	v_add_f32_e32 v198, 1.0, v198
	v_add_f32_e32 v199, 1.0, v199
	v_rcp_f32_e32 v192, v192
	v_rcp_f32_e32 v193, v193
	v_rcp_f32_e32 v194, v194
	v_rcp_f32_e32 v195, v195
	v_rcp_f32_e32 v196, v196
	v_rcp_f32_e32 v197, v197
	v_rcp_f32_e32 v198, v198
	v_rcp_f32_e32 v199, v199
	v_mul_f32_e32 v84, v84, v192
	v_mul_f32_e32 v85, v85, v193
	v_mul_f32_e32 v86, v86, v194
	v_mul_f32_e32 v87, v87, v195
	v_mul_f32_e32 v80, v80, v196
	v_mul_f32_e32 v81, v81, v197
	v_mul_f32_e32 v82, v82, v198
	v_mul_f32_e32 v83, v83, v199
	v_cvt_pk_bf16_f32 v188, v84, v85
	v_cvt_pk_bf16_f32 v189, v86, v87
	v_cvt_pk_bf16_f32 v190, v80, v81
	v_cvt_pk_bf16_f32 v191, v82, v83
	global_store_dwordx4 v181, v[188:191], s[62:63] offset:256
	s_add_u32 s62, s12, 0x90000
	s_addc_u32 s63, s13, 0
	v_mul_f32_e32 v192, 0xbfb8aa3b, v76
	v_mul_f32_e32 v193, 0xbfb8aa3b, v77
	v_mul_f32_e32 v194, 0xbfb8aa3b, v78
	v_mul_f32_e32 v195, 0xbfb8aa3b, v79
	v_mul_f32_e32 v196, 0xbfb8aa3b, v72
	v_mul_f32_e32 v197, 0xbfb8aa3b, v73
	v_mul_f32_e32 v198, 0xbfb8aa3b, v74
	v_mul_f32_e32 v199, 0xbfb8aa3b, v75
	v_exp_f32_e32 v192, v192
	v_exp_f32_e32 v193, v193
	v_exp_f32_e32 v194, v194
	v_exp_f32_e32 v195, v195
	v_exp_f32_e32 v196, v196
	v_exp_f32_e32 v197, v197
	v_exp_f32_e32 v198, v198
	v_exp_f32_e32 v199, v199
	v_add_f32_e32 v192, 1.0, v192
	v_add_f32_e32 v193, 1.0, v193
	v_add_f32_e32 v194, 1.0, v194
	v_add_f32_e32 v195, 1.0, v195
	v_add_f32_e32 v196, 1.0, v196
	v_add_f32_e32 v197, 1.0, v197
	v_add_f32_e32 v198, 1.0, v198
	v_add_f32_e32 v199, 1.0, v199
	v_rcp_f32_e32 v192, v192
	v_rcp_f32_e32 v193, v193
	v_rcp_f32_e32 v194, v194
	v_rcp_f32_e32 v195, v195
	v_rcp_f32_e32 v196, v196
	v_rcp_f32_e32 v197, v197
	v_rcp_f32_e32 v198, v198
	v_rcp_f32_e32 v199, v199
	v_mul_f32_e32 v76, v76, v192
	v_mul_f32_e32 v77, v77, v193
	v_mul_f32_e32 v78, v78, v194
	v_mul_f32_e32 v79, v79, v195
	v_mul_f32_e32 v72, v72, v196
	v_mul_f32_e32 v73, v73, v197
	v_mul_f32_e32 v74, v74, v198
	v_mul_f32_e32 v75, v75, v199
	v_cvt_pk_bf16_f32 v184, v76, v77
	v_cvt_pk_bf16_f32 v185, v78, v79
	v_cvt_pk_bf16_f32 v186, v72, v73
	v_cvt_pk_bf16_f32 v187, v74, v75
	global_store_dwordx4 v181, v[184:187], s[62:63] offset:0
	v_mul_f32_e32 v192, 0xbfb8aa3b, v68
	v_mul_f32_e32 v193, 0xbfb8aa3b, v69
	v_mul_f32_e32 v194, 0xbfb8aa3b, v70
	v_mul_f32_e32 v195, 0xbfb8aa3b, v71
	v_mul_f32_e32 v196, 0xbfb8aa3b, v64
	v_mul_f32_e32 v197, 0xbfb8aa3b, v65
	v_mul_f32_e32 v198, 0xbfb8aa3b, v66
	v_mul_f32_e32 v199, 0xbfb8aa3b, v67
	v_exp_f32_e32 v192, v192
	v_exp_f32_e32 v193, v193
	v_exp_f32_e32 v194, v194
	v_exp_f32_e32 v195, v195
	v_exp_f32_e32 v196, v196
	v_exp_f32_e32 v197, v197
	v_exp_f32_e32 v198, v198
	v_exp_f32_e32 v199, v199
	v_add_f32_e32 v192, 1.0, v192
	v_add_f32_e32 v193, 1.0, v193
	v_add_f32_e32 v194, 1.0, v194
	v_add_f32_e32 v195, 1.0, v195
	v_add_f32_e32 v196, 1.0, v196
	v_add_f32_e32 v197, 1.0, v197
	v_add_f32_e32 v198, 1.0, v198
	v_add_f32_e32 v199, 1.0, v199
	v_rcp_f32_e32 v192, v192
	v_rcp_f32_e32 v193, v193
	v_rcp_f32_e32 v194, v194
	v_rcp_f32_e32 v195, v195
	v_rcp_f32_e32 v196, v196
	v_rcp_f32_e32 v197, v197
	v_rcp_f32_e32 v198, v198
	v_rcp_f32_e32 v199, v199
	v_mul_f32_e32 v68, v68, v192
	v_mul_f32_e32 v69, v69, v193
	v_mul_f32_e32 v70, v70, v194
	v_mul_f32_e32 v71, v71, v195
	v_mul_f32_e32 v64, v64, v196
	v_mul_f32_e32 v65, v65, v197
	v_mul_f32_e32 v66, v66, v198
	v_mul_f32_e32 v67, v67, v199
	v_cvt_pk_bf16_f32 v188, v68, v69
	v_cvt_pk_bf16_f32 v189, v70, v71
	v_cvt_pk_bf16_f32 v190, v64, v65
	v_cvt_pk_bf16_f32 v191, v66, v67
	global_store_dwordx4 v181, v[188:191], s[62:63] offset:256
	s_add_u32 s62, s12, 0x180000
	s_addc_u32 s63, s13, 0
	v_mul_f32_e32 v192, 0xbfb8aa3b, v60
	v_mul_f32_e32 v193, 0xbfb8aa3b, v61
	v_mul_f32_e32 v194, 0xbfb8aa3b, v62
	v_mul_f32_e32 v195, 0xbfb8aa3b, v63
	v_mul_f32_e32 v196, 0xbfb8aa3b, v56
	v_mul_f32_e32 v197, 0xbfb8aa3b, v57
	v_mul_f32_e32 v198, 0xbfb8aa3b, v58
	v_mul_f32_e32 v199, 0xbfb8aa3b, v59
	v_exp_f32_e32 v192, v192
	v_exp_f32_e32 v193, v193
	v_exp_f32_e32 v194, v194
	v_exp_f32_e32 v195, v195
	v_exp_f32_e32 v196, v196
	v_exp_f32_e32 v197, v197
	v_exp_f32_e32 v198, v198
	v_exp_f32_e32 v199, v199
	v_add_f32_e32 v192, 1.0, v192
	v_add_f32_e32 v193, 1.0, v193
	v_add_f32_e32 v194, 1.0, v194
	v_add_f32_e32 v195, 1.0, v195
	v_add_f32_e32 v196, 1.0, v196
	v_add_f32_e32 v197, 1.0, v197
	v_add_f32_e32 v198, 1.0, v198
	v_add_f32_e32 v199, 1.0, v199
	v_rcp_f32_e32 v192, v192
	v_rcp_f32_e32 v193, v193
	v_rcp_f32_e32 v194, v194
	v_rcp_f32_e32 v195, v195
	v_rcp_f32_e32 v196, v196
	v_rcp_f32_e32 v197, v197
	v_rcp_f32_e32 v198, v198
	v_rcp_f32_e32 v199, v199
	v_mul_f32_e32 v60, v60, v192
	v_mul_f32_e32 v61, v61, v193
	v_mul_f32_e32 v62, v62, v194
	v_mul_f32_e32 v63, v63, v195
	v_mul_f32_e32 v56, v56, v196
	v_mul_f32_e32 v57, v57, v197
	v_mul_f32_e32 v58, v58, v198
	v_mul_f32_e32 v59, v59, v199
	v_cvt_pk_bf16_f32 v184, v60, v61
	v_cvt_pk_bf16_f32 v185, v62, v63
	v_cvt_pk_bf16_f32 v186, v56, v57
	v_cvt_pk_bf16_f32 v187, v58, v59
	global_store_dwordx4 v181, v[184:187], s[62:63] offset:0
	v_mul_f32_e32 v192, 0xbfb8aa3b, v52
	v_mul_f32_e32 v193, 0xbfb8aa3b, v53
	v_mul_f32_e32 v194, 0xbfb8aa3b, v54
	v_mul_f32_e32 v195, 0xbfb8aa3b, v55
	v_mul_f32_e32 v196, 0xbfb8aa3b, v48
	v_mul_f32_e32 v197, 0xbfb8aa3b, v49
	v_mul_f32_e32 v198, 0xbfb8aa3b, v50
	v_mul_f32_e32 v199, 0xbfb8aa3b, v51
	v_exp_f32_e32 v192, v192
	v_exp_f32_e32 v193, v193
	v_exp_f32_e32 v194, v194
	v_exp_f32_e32 v195, v195
	v_exp_f32_e32 v196, v196
	v_exp_f32_e32 v197, v197
	v_exp_f32_e32 v198, v198
	v_exp_f32_e32 v199, v199
	v_add_f32_e32 v192, 1.0, v192
	v_add_f32_e32 v193, 1.0, v193
	v_add_f32_e32 v194, 1.0, v194
	v_add_f32_e32 v195, 1.0, v195
	v_add_f32_e32 v196, 1.0, v196
	v_add_f32_e32 v197, 1.0, v197
	v_add_f32_e32 v198, 1.0, v198
	v_add_f32_e32 v199, 1.0, v199
	v_rcp_f32_e32 v192, v192
	v_rcp_f32_e32 v193, v193
	v_rcp_f32_e32 v194, v194
	v_rcp_f32_e32 v195, v195
	v_rcp_f32_e32 v196, v196
	v_rcp_f32_e32 v197, v197
	v_rcp_f32_e32 v198, v198
	v_rcp_f32_e32 v199, v199
	v_mul_f32_e32 v52, v52, v192
	v_mul_f32_e32 v53, v53, v193
	v_mul_f32_e32 v54, v54, v194
	v_mul_f32_e32 v55, v55, v195
	v_mul_f32_e32 v48, v48, v196
	v_mul_f32_e32 v49, v49, v197
	v_mul_f32_e32 v50, v50, v198
	v_mul_f32_e32 v51, v51, v199
	v_cvt_pk_bf16_f32 v188, v52, v53
	v_cvt_pk_bf16_f32 v189, v54, v55
	v_cvt_pk_bf16_f32 v190, v48, v49
	v_cvt_pk_bf16_f32 v191, v50, v51
	global_store_dwordx4 v181, v[188:191], s[62:63] offset:256
	s_add_u32 s62, s12, 0x1b0000
	s_addc_u32 s63, s13, 0
	v_mul_f32_e32 v192, 0xbfb8aa3b, v44
	v_mul_f32_e32 v193, 0xbfb8aa3b, v45
	v_mul_f32_e32 v194, 0xbfb8aa3b, v46
	v_mul_f32_e32 v195, 0xbfb8aa3b, v47
	v_mul_f32_e32 v196, 0xbfb8aa3b, v40
	v_mul_f32_e32 v197, 0xbfb8aa3b, v41
	v_mul_f32_e32 v198, 0xbfb8aa3b, v42
	v_mul_f32_e32 v199, 0xbfb8aa3b, v43
	v_exp_f32_e32 v192, v192
	v_exp_f32_e32 v193, v193
	v_exp_f32_e32 v194, v194
	v_exp_f32_e32 v195, v195
	v_exp_f32_e32 v196, v196
	v_exp_f32_e32 v197, v197
	v_exp_f32_e32 v198, v198
	v_exp_f32_e32 v199, v199
	v_add_f32_e32 v192, 1.0, v192
	v_add_f32_e32 v193, 1.0, v193
	v_add_f32_e32 v194, 1.0, v194
	v_add_f32_e32 v195, 1.0, v195
	v_add_f32_e32 v196, 1.0, v196
	v_add_f32_e32 v197, 1.0, v197
	v_add_f32_e32 v198, 1.0, v198
	v_add_f32_e32 v199, 1.0, v199
	v_rcp_f32_e32 v192, v192
	v_rcp_f32_e32 v193, v193
	v_rcp_f32_e32 v194, v194
	v_rcp_f32_e32 v195, v195
	v_rcp_f32_e32 v196, v196
	v_rcp_f32_e32 v197, v197
	v_rcp_f32_e32 v198, v198
	v_rcp_f32_e32 v199, v199
	v_mul_f32_e32 v44, v44, v192
	v_mul_f32_e32 v45, v45, v193
	v_mul_f32_e32 v46, v46, v194
	v_mul_f32_e32 v47, v47, v195
	v_mul_f32_e32 v40, v40, v196
	v_mul_f32_e32 v41, v41, v197
	v_mul_f32_e32 v42, v42, v198
	v_mul_f32_e32 v43, v43, v199
	v_cvt_pk_bf16_f32 v184, v44, v45
	v_cvt_pk_bf16_f32 v185, v46, v47
	v_cvt_pk_bf16_f32 v186, v40, v41
	v_cvt_pk_bf16_f32 v187, v42, v43
	global_store_dwordx4 v181, v[184:187], s[62:63] offset:0
	v_mul_f32_e32 v192, 0xbfb8aa3b, v36
	v_mul_f32_e32 v193, 0xbfb8aa3b, v37
	v_mul_f32_e32 v194, 0xbfb8aa3b, v38
	v_mul_f32_e32 v195, 0xbfb8aa3b, v39
	v_mul_f32_e32 v196, 0xbfb8aa3b, v32
	v_mul_f32_e32 v197, 0xbfb8aa3b, v33
	v_mul_f32_e32 v198, 0xbfb8aa3b, v34
	v_mul_f32_e32 v199, 0xbfb8aa3b, v35
	v_exp_f32_e32 v192, v192
	v_exp_f32_e32 v193, v193
	v_exp_f32_e32 v194, v194
	v_exp_f32_e32 v195, v195
	v_exp_f32_e32 v196, v196
	v_exp_f32_e32 v197, v197
	v_exp_f32_e32 v198, v198
	v_exp_f32_e32 v199, v199
	v_add_f32_e32 v192, 1.0, v192
	v_add_f32_e32 v193, 1.0, v193
	v_add_f32_e32 v194, 1.0, v194
	v_add_f32_e32 v195, 1.0, v195
	v_add_f32_e32 v196, 1.0, v196
	v_add_f32_e32 v197, 1.0, v197
	v_add_f32_e32 v198, 1.0, v198
	v_add_f32_e32 v199, 1.0, v199
	v_rcp_f32_e32 v192, v192
	v_rcp_f32_e32 v193, v193
	v_rcp_f32_e32 v194, v194
	v_rcp_f32_e32 v195, v195
	v_rcp_f32_e32 v196, v196
	v_rcp_f32_e32 v197, v197
	v_rcp_f32_e32 v198, v198
	v_rcp_f32_e32 v199, v199
	v_mul_f32_e32 v36, v36, v192
	v_mul_f32_e32 v37, v37, v193
	v_mul_f32_e32 v38, v38, v194
	v_mul_f32_e32 v39, v39, v195
	v_mul_f32_e32 v32, v32, v196
	v_mul_f32_e32 v33, v33, v197
	v_mul_f32_e32 v34, v34, v198
	v_mul_f32_e32 v35, v35, v199
	v_cvt_pk_bf16_f32 v188, v36, v37
	v_cvt_pk_bf16_f32 v189, v38, v39
	v_cvt_pk_bf16_f32 v190, v32, v33
	v_cvt_pk_bf16_f32 v191, v34, v35
	global_store_dwordx4 v181, v[188:191], s[62:63] offset:256
	s_add_u32 s62, s12, 0x1e0000
	s_addc_u32 s63, s13, 0
	v_mul_f32_e32 v192, 0xbfb8aa3b, v28
	v_mul_f32_e32 v193, 0xbfb8aa3b, v29
	v_mul_f32_e32 v194, 0xbfb8aa3b, v30
	v_mul_f32_e32 v195, 0xbfb8aa3b, v31
	v_mul_f32_e32 v196, 0xbfb8aa3b, v24
	v_mul_f32_e32 v197, 0xbfb8aa3b, v25
	v_mul_f32_e32 v198, 0xbfb8aa3b, v26
	v_mul_f32_e32 v199, 0xbfb8aa3b, v27
	v_exp_f32_e32 v192, v192
	v_exp_f32_e32 v193, v193
	v_exp_f32_e32 v194, v194
	v_exp_f32_e32 v195, v195
	v_exp_f32_e32 v196, v196
	v_exp_f32_e32 v197, v197
	v_exp_f32_e32 v198, v198
	v_exp_f32_e32 v199, v199
	v_add_f32_e32 v192, 1.0, v192
	v_add_f32_e32 v193, 1.0, v193
	v_add_f32_e32 v194, 1.0, v194
	v_add_f32_e32 v195, 1.0, v195
	v_add_f32_e32 v196, 1.0, v196
	v_add_f32_e32 v197, 1.0, v197
	v_add_f32_e32 v198, 1.0, v198
	v_add_f32_e32 v199, 1.0, v199
	v_rcp_f32_e32 v192, v192
	v_rcp_f32_e32 v193, v193
	v_rcp_f32_e32 v194, v194
	v_rcp_f32_e32 v195, v195
	v_rcp_f32_e32 v196, v196
	v_rcp_f32_e32 v197, v197
	v_rcp_f32_e32 v198, v198
	v_rcp_f32_e32 v199, v199
	v_mul_f32_e32 v28, v28, v192
	v_mul_f32_e32 v29, v29, v193
	v_mul_f32_e32 v30, v30, v194
	v_mul_f32_e32 v31, v31, v195
	v_mul_f32_e32 v24, v24, v196
	v_mul_f32_e32 v25, v25, v197
	v_mul_f32_e32 v26, v26, v198
	v_mul_f32_e32 v27, v27, v199
	v_cvt_pk_bf16_f32 v184, v28, v29
	v_cvt_pk_bf16_f32 v185, v30, v31
	v_cvt_pk_bf16_f32 v186, v24, v25
	v_cvt_pk_bf16_f32 v187, v26, v27
	global_store_dwordx4 v181, v[184:187], s[62:63] offset:0
	v_mul_f32_e32 v192, 0xbfb8aa3b, v20
	v_mul_f32_e32 v193, 0xbfb8aa3b, v21
	v_mul_f32_e32 v194, 0xbfb8aa3b, v22
	v_mul_f32_e32 v195, 0xbfb8aa3b, v23
	v_mul_f32_e32 v196, 0xbfb8aa3b, v16
	v_mul_f32_e32 v197, 0xbfb8aa3b, v17
	v_mul_f32_e32 v198, 0xbfb8aa3b, v18
	v_mul_f32_e32 v199, 0xbfb8aa3b, v19
	v_exp_f32_e32 v192, v192
	v_exp_f32_e32 v193, v193
	v_exp_f32_e32 v194, v194
	v_exp_f32_e32 v195, v195
	v_exp_f32_e32 v196, v196
	v_exp_f32_e32 v197, v197
	v_exp_f32_e32 v198, v198
	v_exp_f32_e32 v199, v199
	v_add_f32_e32 v192, 1.0, v192
	v_add_f32_e32 v193, 1.0, v193
	v_add_f32_e32 v194, 1.0, v194
	v_add_f32_e32 v195, 1.0, v195
	v_add_f32_e32 v196, 1.0, v196
	v_add_f32_e32 v197, 1.0, v197
	v_add_f32_e32 v198, 1.0, v198
	v_add_f32_e32 v199, 1.0, v199
	v_rcp_f32_e32 v192, v192
	v_rcp_f32_e32 v193, v193
	v_rcp_f32_e32 v194, v194
	v_rcp_f32_e32 v195, v195
	v_rcp_f32_e32 v196, v196
	v_rcp_f32_e32 v197, v197
	v_rcp_f32_e32 v198, v198
	v_rcp_f32_e32 v199, v199
	v_mul_f32_e32 v20, v20, v192
	v_mul_f32_e32 v21, v21, v193
	v_mul_f32_e32 v22, v22, v194
	v_mul_f32_e32 v23, v23, v195
	v_mul_f32_e32 v16, v16, v196
	v_mul_f32_e32 v17, v17, v197
	v_mul_f32_e32 v18, v18, v198
	v_mul_f32_e32 v19, v19, v199
	v_cvt_pk_bf16_f32 v188, v20, v21
	v_cvt_pk_bf16_f32 v189, v22, v23
	v_cvt_pk_bf16_f32 v190, v16, v17
	v_cvt_pk_bf16_f32 v191, v18, v19
	global_store_dwordx4 v181, v[188:191], s[62:63] offset:256
	s_add_u32 s62, s12, 0x210000
	s_addc_u32 s63, s13, 0
	v_mul_f32_e32 v192, 0xbfb8aa3b, v12
	v_mul_f32_e32 v193, 0xbfb8aa3b, v13
	v_mul_f32_e32 v194, 0xbfb8aa3b, v14
	v_mul_f32_e32 v195, 0xbfb8aa3b, v15
	v_mul_f32_e32 v196, 0xbfb8aa3b, v8
	v_mul_f32_e32 v197, 0xbfb8aa3b, v9
	v_mul_f32_e32 v198, 0xbfb8aa3b, v10
	v_mul_f32_e32 v199, 0xbfb8aa3b, v11
	v_exp_f32_e32 v192, v192
	v_exp_f32_e32 v193, v193
	v_exp_f32_e32 v194, v194
	v_exp_f32_e32 v195, v195
	v_exp_f32_e32 v196, v196
	v_exp_f32_e32 v197, v197
	v_exp_f32_e32 v198, v198
	v_exp_f32_e32 v199, v199
	v_add_f32_e32 v192, 1.0, v192
	v_add_f32_e32 v193, 1.0, v193
	v_add_f32_e32 v194, 1.0, v194
	v_add_f32_e32 v195, 1.0, v195
	v_add_f32_e32 v196, 1.0, v196
	v_add_f32_e32 v197, 1.0, v197
	v_add_f32_e32 v198, 1.0, v198
	v_add_f32_e32 v199, 1.0, v199
	v_rcp_f32_e32 v192, v192
	v_rcp_f32_e32 v193, v193
	v_rcp_f32_e32 v194, v194
	v_rcp_f32_e32 v195, v195
	v_rcp_f32_e32 v196, v196
	v_rcp_f32_e32 v197, v197
	v_rcp_f32_e32 v198, v198
	v_rcp_f32_e32 v199, v199
	v_mul_f32_e32 v12, v12, v192
	v_mul_f32_e32 v13, v13, v193
	v_mul_f32_e32 v14, v14, v194
	v_mul_f32_e32 v15, v15, v195
	v_mul_f32_e32 v8, v8, v196
	v_mul_f32_e32 v9, v9, v197
	v_mul_f32_e32 v10, v10, v198
	v_mul_f32_e32 v11, v11, v199
	v_cvt_pk_bf16_f32 v184, v12, v13
	v_cvt_pk_bf16_f32 v185, v14, v15
	v_cvt_pk_bf16_f32 v186, v8, v9
	v_cvt_pk_bf16_f32 v187, v10, v11
	global_store_dwordx4 v181, v[184:187], s[62:63] offset:0
	v_mul_f32_e32 v192, 0xbfb8aa3b, v4
	v_mul_f32_e32 v193, 0xbfb8aa3b, v5
	v_mul_f32_e32 v194, 0xbfb8aa3b, v6
	v_mul_f32_e32 v195, 0xbfb8aa3b, v7
	v_mul_f32_e32 v196, 0xbfb8aa3b, v0
	v_mul_f32_e32 v197, 0xbfb8aa3b, v1
	v_mul_f32_e32 v198, 0xbfb8aa3b, v2
	v_mul_f32_e32 v199, 0xbfb8aa3b, v3
	v_exp_f32_e32 v192, v192
	v_exp_f32_e32 v193, v193
	v_exp_f32_e32 v194, v194
	v_exp_f32_e32 v195, v195
	v_exp_f32_e32 v196, v196
	v_exp_f32_e32 v197, v197
	v_exp_f32_e32 v198, v198
	v_exp_f32_e32 v199, v199
	v_add_f32_e32 v192, 1.0, v192
	v_add_f32_e32 v193, 1.0, v193
	v_add_f32_e32 v194, 1.0, v194
	v_add_f32_e32 v195, 1.0, v195
	v_add_f32_e32 v196, 1.0, v196
	v_add_f32_e32 v197, 1.0, v197
	v_add_f32_e32 v198, 1.0, v198
	v_add_f32_e32 v199, 1.0, v199
	v_rcp_f32_e32 v192, v192
	v_rcp_f32_e32 v193, v193
	v_rcp_f32_e32 v194, v194
	v_rcp_f32_e32 v195, v195
	v_rcp_f32_e32 v196, v196
	v_rcp_f32_e32 v197, v197
	v_rcp_f32_e32 v198, v198
	v_rcp_f32_e32 v199, v199
	v_mul_f32_e32 v4, v4, v192
	v_mul_f32_e32 v5, v5, v193
	v_mul_f32_e32 v6, v6, v194
	v_mul_f32_e32 v7, v7, v195
	v_mul_f32_e32 v0, v0, v196
	v_mul_f32_e32 v1, v1, v197
	v_mul_f32_e32 v2, v2, v198
	v_mul_f32_e32 v3, v3, v199
	v_cvt_pk_bf16_f32 v188, v4, v5
	v_cvt_pk_bf16_f32 v189, v6, v7
	v_cvt_pk_bf16_f32 v190, v0, v1
	v_cvt_pk_bf16_f32 v191, v2, v3
	global_store_dwordx4 v181, v[188:191], s[62:63] offset:256
	s_branch .Lep_fast_done
.Lep_kind1:
	v_and_b32_e32 v181, 0x7ff, v180
	v_lshlrev_b32_e32 v181, 8, v181
	v_lshl_add_u32 v181, v146, 1, v181
	s_lshr_b32 s61, s60, 3
	s_lshl_b32 s61, s61, 3
	s_and_b32 s68, s16, 3
	s_lshl_b32 s68, s68, 1
	s_add_i32 s61, s61, s68
	s_lshl_b32 s61, s61, 19
	s_add_u32 s66, s14, s61
	s_addc_u32 s67, s15, 0
	s_add_u32 s62, s66, 0x0
	s_addc_u32 s63, s67, 0
	s_add_u32 s64, s66, 0x80000
	s_addc_u32 s65, s67, 0
	v_cvt_pk_bf16_f32 v184, v124, v125
	v_cvt_pk_bf16_f32 v185, v126, v127
	v_cvt_pk_bf16_f32 v186, v120, v121
	v_cvt_pk_bf16_f32 v187, v122, v123
	global_store_dwordx4 v181, v[184:187], s[62:63]
	v_cvt_pk_bf16_f32 v188, v116, v117
	v_cvt_pk_bf16_f32 v189, v118, v119
	v_cvt_pk_bf16_f32 v190, v112, v113
	v_cvt_pk_bf16_f32 v191, v114, v115
	global_store_dwordx4 v181, v[188:191], s[64:65]
	s_add_u32 s62, s66, 0x1000
	s_addc_u32 s63, s67, 0
	s_add_u32 s64, s66, 0x81000
	s_addc_u32 s65, s67, 0
	v_cvt_pk_bf16_f32 v184, v108, v109
	v_cvt_pk_bf16_f32 v185, v110, v111
	v_cvt_pk_bf16_f32 v186, v104, v105
	v_cvt_pk_bf16_f32 v187, v106, v107
	global_store_dwordx4 v181, v[184:187], s[62:63]
	v_cvt_pk_bf16_f32 v188, v100, v101
	v_cvt_pk_bf16_f32 v189, v102, v103
	v_cvt_pk_bf16_f32 v190, v96, v97
	v_cvt_pk_bf16_f32 v191, v98, v99
	global_store_dwordx4 v181, v[188:191], s[64:65]
	s_add_u32 s62, s66, 0x2000
	s_addc_u32 s63, s67, 0
	s_add_u32 s64, s66, 0x82000
	s_addc_u32 s65, s67, 0
	v_cvt_pk_bf16_f32 v184, v92, v93
	v_cvt_pk_bf16_f32 v185, v94, v95
	v_cvt_pk_bf16_f32 v186, v88, v89
	v_cvt_pk_bf16_f32 v187, v90, v91
	global_store_dwordx4 v181, v[184:187], s[62:63]
	v_cvt_pk_bf16_f32 v188, v84, v85
	v_cvt_pk_bf16_f32 v189, v86, v87
	v_cvt_pk_bf16_f32 v190, v80, v81
	v_cvt_pk_bf16_f32 v191, v82, v83
	global_store_dwordx4 v181, v[188:191], s[64:65]
	s_add_u32 s62, s66, 0x3000
	s_addc_u32 s63, s67, 0
	s_add_u32 s64, s66, 0x83000
	s_addc_u32 s65, s67, 0
	v_cvt_pk_bf16_f32 v184, v76, v77
	v_cvt_pk_bf16_f32 v185, v78, v79
	v_cvt_pk_bf16_f32 v186, v72, v73
	v_cvt_pk_bf16_f32 v187, v74, v75
	global_store_dwordx4 v181, v[184:187], s[62:63]
	v_cvt_pk_bf16_f32 v188, v68, v69
	v_cvt_pk_bf16_f32 v189, v70, v71
	v_cvt_pk_bf16_f32 v190, v64, v65
	v_cvt_pk_bf16_f32 v191, v66, v67
	global_store_dwordx4 v181, v[188:191], s[64:65]
	s_add_u32 s62, s66, 0x8000
	s_addc_u32 s63, s67, 0
	s_add_u32 s64, s66, 0x88000
	s_addc_u32 s65, s67, 0
	v_cvt_pk_bf16_f32 v184, v60, v61
	v_cvt_pk_bf16_f32 v185, v62, v63
	v_cvt_pk_bf16_f32 v186, v56, v57
	v_cvt_pk_bf16_f32 v187, v58, v59
	global_store_dwordx4 v181, v[184:187], s[62:63]
	v_cvt_pk_bf16_f32 v188, v52, v53
	v_cvt_pk_bf16_f32 v189, v54, v55
	v_cvt_pk_bf16_f32 v190, v48, v49
	v_cvt_pk_bf16_f32 v191, v50, v51
	global_store_dwordx4 v181, v[188:191], s[64:65]
	s_add_u32 s62, s66, 0x9000
	s_addc_u32 s63, s67, 0
	s_add_u32 s64, s66, 0x89000
	s_addc_u32 s65, s67, 0
	v_cvt_pk_bf16_f32 v184, v44, v45
	v_cvt_pk_bf16_f32 v185, v46, v47
	v_cvt_pk_bf16_f32 v186, v40, v41
	v_cvt_pk_bf16_f32 v187, v42, v43
	global_store_dwordx4 v181, v[184:187], s[62:63]
	v_cvt_pk_bf16_f32 v188, v36, v37
	v_cvt_pk_bf16_f32 v189, v38, v39
	v_cvt_pk_bf16_f32 v190, v32, v33
	v_cvt_pk_bf16_f32 v191, v34, v35
	global_store_dwordx4 v181, v[188:191], s[64:65]
	s_add_u32 s62, s66, 0xa000
	s_addc_u32 s63, s67, 0
	s_add_u32 s64, s66, 0x8a000
	s_addc_u32 s65, s67, 0
	v_cvt_pk_bf16_f32 v184, v28, v29
	v_cvt_pk_bf16_f32 v185, v30, v31
	v_cvt_pk_bf16_f32 v186, v24, v25
	v_cvt_pk_bf16_f32 v187, v26, v27
	global_store_dwordx4 v181, v[184:187], s[62:63]
	v_cvt_pk_bf16_f32 v188, v20, v21
	v_cvt_pk_bf16_f32 v189, v22, v23
	v_cvt_pk_bf16_f32 v190, v16, v17
	v_cvt_pk_bf16_f32 v191, v18, v19
	global_store_dwordx4 v181, v[188:191], s[64:65]
	s_add_u32 s62, s66, 0xb000
	s_addc_u32 s63, s67, 0
	s_add_u32 s64, s66, 0x8b000
	s_addc_u32 s65, s67, 0
	v_cvt_pk_bf16_f32 v184, v12, v13
	v_cvt_pk_bf16_f32 v185, v14, v15
	v_cvt_pk_bf16_f32 v186, v8, v9
	v_cvt_pk_bf16_f32 v187, v10, v11
	global_store_dwordx4 v181, v[184:187], s[62:63]
	v_cvt_pk_bf16_f32 v188, v4, v5
	v_cvt_pk_bf16_f32 v189, v6, v7
	v_cvt_pk_bf16_f32 v190, v0, v1
	v_cvt_pk_bf16_f32 v191, v2, v3
	global_store_dwordx4 v181, v[188:191], s[64:65]
	s_branch .Lep_fast_done
.Lep_kind3:
	s_mov_b64 s[96:97], exec
	s_and_b64 s[68:69], s[48:49], s[6:7]
	s_cbranch_scc0 .Lep_kind3n
	v_and_b32_e32 v182, 0x7ff, v180
	v_lshlrev_b32_e32 v182, 6, v182
	v_lshl_add_u32 v182, v164, 2, v182
	s_mov_b64 s[98:99], s[44:45]
	s_mov_b64 exec, s[68:69]
	global_load_dwordx4 v[200:203], v182, s[98:99]
	global_load_dwordx4 v[204:207], v182, s[98:99] offset:16
	s_mov_b64 exec, s[96:97]
	s_add_u32 s98, s44, 0x400
	s_addc_u32 s99, s45, 0
	s_mov_b64 exec, s[68:69]
	global_load_dwordx4 v[208:211], v182, s[98:99]
	global_load_dwordx4 v[212:215], v182, s[98:99] offset:16
	s_mov_b64 exec, s[96:97]
	s_add_u32 s98, s44, 0x800
	s_addc_u32 s99, s45, 0
	s_mov_b64 exec, s[68:69]
	global_load_dwordx4 v[216:219], v182, s[98:99]
	global_load_dwordx4 v[220:223], v182, s[98:99] offset:16
	s_mov_b64 exec, s[96:97]
	s_add_u32 s98, s44, 0xc00
	s_addc_u32 s99, s45, 0
	s_mov_b64 exec, s[68:69]
	global_load_dwordx4 v[226:229], v182, s[98:99]
	global_load_dwordx4 v[230:233], v182, s[98:99] offset:16
	s_mov_b64 exec, s[96:97]
	s_mov_b64 s[62:63], s[12:13]
	s_waitcnt vmcnt(6)
	s_mov_b64 exec, s[68:69]
	v_mul_f32_e32 v183, v125, v201
	v_mul_f32_e32 v234, v124, v201
	v_fma_f32 v124, v124, v200, -v183
	v_fma_f32 v125, v125, v200, v234
	v_mul_f32_e32 v183, v127, v203
	v_mul_f32_e32 v234, v126, v203
	v_fma_f32 v126, v126, v202, -v183
	v_fma_f32 v127, v127, v202, v234
	v_mul_f32_e32 v183, v121, v205
	v_mul_f32_e32 v234, v120, v205
	v_fma_f32 v120, v120, v204, -v183
	v_fma_f32 v121, v121, v204, v234
	v_mul_f32_e32 v183, v123, v207
	v_mul_f32_e32 v234, v122, v207
	v_fma_f32 v122, v122, v206, -v183
	v_fma_f32 v123, v123, v206, v234
	s_mov_b64 exec, s[96:97]
	v_mul_f32_e32 v124, v169, v124
	v_mul_f32_e32 v125, v169, v125
	v_mul_f32_e32 v126, v169, v126
	v_mul_f32_e32 v127, v169, v127
	v_mul_f32_e32 v120, v169, v120
	v_mul_f32_e32 v121, v169, v121
	v_mul_f32_e32 v122, v169, v122
	v_mul_f32_e32 v123, v169, v123
	v_cvt_pk_bf16_f32 v184, v124, v125
	v_cvt_pk_bf16_f32 v185, v126, v127
	v_cvt_pk_bf16_f32 v186, v120, v121
	v_cvt_pk_bf16_f32 v187, v122, v123
	global_store_dwordx4 v181, v[184:187], s[62:63] offset:0
	s_mov_b64 exec, s[68:69]
	v_mul_f32_e32 v183, v117, v201
	v_mul_f32_e32 v234, v116, v201
	v_fma_f32 v116, v116, v200, -v183
	v_fma_f32 v117, v117, v200, v234
	v_mul_f32_e32 v183, v119, v203
	v_mul_f32_e32 v234, v118, v203
	v_fma_f32 v118, v118, v202, -v183
	v_fma_f32 v119, v119, v202, v234
	v_mul_f32_e32 v183, v113, v205
	v_mul_f32_e32 v234, v112, v205
	v_fma_f32 v112, v112, v204, -v183
	v_fma_f32 v113, v113, v204, v234
	v_mul_f32_e32 v183, v115, v207
	v_mul_f32_e32 v234, v114, v207
	v_fma_f32 v114, v114, v206, -v183
	v_fma_f32 v115, v115, v206, v234
	s_mov_b64 exec, s[96:97]
	v_mul_f32_e32 v116, v169, v116
	v_mul_f32_e32 v117, v169, v117
	v_mul_f32_e32 v118, v169, v118
	v_mul_f32_e32 v119, v169, v119
	v_mul_f32_e32 v112, v169, v112
	v_mul_f32_e32 v113, v169, v113
	v_mul_f32_e32 v114, v169, v114
	v_mul_f32_e32 v115, v169, v115
	v_cvt_pk_bf16_f32 v188, v116, v117
	v_cvt_pk_bf16_f32 v189, v118, v119
	v_cvt_pk_bf16_f32 v190, v112, v113
	v_cvt_pk_bf16_f32 v191, v114, v115
	global_store_dwordx4 v181, v[188:191], s[62:63] offset:256
	s_add_u32 s98, s44, 0x2000
	s_addc_u32 s99, s45, 0
	s_mov_b64 exec, s[68:69]
	global_load_dwordx4 v[200:203], v182, s[98:99]
	global_load_dwordx4 v[204:207], v182, s[98:99] offset:16
	s_mov_b64 exec, s[96:97]
	s_add_u32 s62, s12, 0x30000
	s_addc_u32 s63, s13, 0
	s_waitcnt vmcnt(8)
	s_mov_b64 exec, s[68:69]
	v_mul_f32_e32 v183, v109, v209
	v_mul_f32_e32 v234, v108, v209
	v_fma_f32 v108, v108, v208, -v183
	v_fma_f32 v109, v109, v208, v234
	v_mul_f32_e32 v183, v111, v211
	v_mul_f32_e32 v234, v110, v211
	v_fma_f32 v110, v110, v210, -v183
	v_fma_f32 v111, v111, v210, v234
	v_mul_f32_e32 v183, v105, v213
	v_mul_f32_e32 v234, v104, v213
	v_fma_f32 v104, v104, v212, -v183
	v_fma_f32 v105, v105, v212, v234
	v_mul_f32_e32 v183, v107, v215
	v_mul_f32_e32 v234, v106, v215
	v_fma_f32 v106, v106, v214, -v183
	v_fma_f32 v107, v107, v214, v234
	s_mov_b64 exec, s[96:97]
	v_mul_f32_e32 v108, v169, v108
	v_mul_f32_e32 v109, v169, v109
	v_mul_f32_e32 v110, v169, v110
	v_mul_f32_e32 v111, v169, v111
	v_mul_f32_e32 v104, v169, v104
	v_mul_f32_e32 v105, v169, v105
	v_mul_f32_e32 v106, v169, v106
	v_mul_f32_e32 v107, v169, v107
	v_cvt_pk_bf16_f32 v184, v108, v109
	v_cvt_pk_bf16_f32 v185, v110, v111
	v_cvt_pk_bf16_f32 v186, v104, v105
	v_cvt_pk_bf16_f32 v187, v106, v107
	global_store_dwordx4 v181, v[184:187], s[62:63] offset:0
	s_mov_b64 exec, s[68:69]
	v_mul_f32_e32 v183, v101, v209
	v_mul_f32_e32 v234, v100, v209
	v_fma_f32 v100, v100, v208, -v183
	v_fma_f32 v101, v101, v208, v234
	v_mul_f32_e32 v183, v103, v211
	v_mul_f32_e32 v234, v102, v211
	v_fma_f32 v102, v102, v210, -v183
	v_fma_f32 v103, v103, v210, v234
	v_mul_f32_e32 v183, v97, v213
	v_mul_f32_e32 v234, v96, v213
	v_fma_f32 v96, v96, v212, -v183
	v_fma_f32 v97, v97, v212, v234
	v_mul_f32_e32 v183, v99, v215
	v_mul_f32_e32 v234, v98, v215
	v_fma_f32 v98, v98, v214, -v183
	v_fma_f32 v99, v99, v214, v234
	s_mov_b64 exec, s[96:97]
	v_mul_f32_e32 v100, v169, v100
	v_mul_f32_e32 v101, v169, v101
	v_mul_f32_e32 v102, v169, v102
	v_mul_f32_e32 v103, v169, v103
	v_mul_f32_e32 v96, v169, v96
	v_mul_f32_e32 v97, v169, v97
	v_mul_f32_e32 v98, v169, v98
	v_mul_f32_e32 v99, v169, v99
	v_cvt_pk_bf16_f32 v188, v100, v101
	v_cvt_pk_bf16_f32 v189, v102, v103
	v_cvt_pk_bf16_f32 v190, v96, v97
	v_cvt_pk_bf16_f32 v191, v98, v99
	global_store_dwordx4 v181, v[188:191], s[62:63] offset:256
	s_add_u32 s98, s44, 0x2400
	s_addc_u32 s99, s45, 0
	s_mov_b64 exec, s[68:69]
	global_load_dwordx4 v[208:211], v182, s[98:99]
	global_load_dwordx4 v[212:215], v182, s[98:99] offset:16
	s_mov_b64 exec, s[96:97]
	s_add_u32 s62, s12, 0x60000
	s_addc_u32 s63, s13, 0
	s_waitcnt vmcnt(10)
	s_mov_b64 exec, s[68:69]
	v_mul_f32_e32 v183, v93, v217
	v_mul_f32_e32 v234, v92, v217
	v_fma_f32 v92, v92, v216, -v183
	v_fma_f32 v93, v93, v216, v234
	v_mul_f32_e32 v183, v95, v219
	v_mul_f32_e32 v234, v94, v219
	v_fma_f32 v94, v94, v218, -v183
	v_fma_f32 v95, v95, v218, v234
	v_mul_f32_e32 v183, v89, v221
	v_mul_f32_e32 v234, v88, v221
	v_fma_f32 v88, v88, v220, -v183
	v_fma_f32 v89, v89, v220, v234
	v_mul_f32_e32 v183, v91, v223
	v_mul_f32_e32 v234, v90, v223
	v_fma_f32 v90, v90, v222, -v183
	v_fma_f32 v91, v91, v222, v234
	s_mov_b64 exec, s[96:97]
	v_mul_f32_e32 v92, v169, v92
	v_mul_f32_e32 v93, v169, v93
	v_mul_f32_e32 v94, v169, v94
	v_mul_f32_e32 v95, v169, v95
	v_mul_f32_e32 v88, v169, v88
	v_mul_f32_e32 v89, v169, v89
	v_mul_f32_e32 v90, v169, v90
	v_mul_f32_e32 v91, v169, v91
	v_cvt_pk_bf16_f32 v184, v92, v93
	v_cvt_pk_bf16_f32 v185, v94, v95
	v_cvt_pk_bf16_f32 v186, v88, v89
	v_cvt_pk_bf16_f32 v187, v90, v91
	global_store_dwordx4 v181, v[184:187], s[62:63] offset:0
	s_mov_b64 exec, s[68:69]
	v_mul_f32_e32 v183, v85, v217
	v_mul_f32_e32 v234, v84, v217
	v_fma_f32 v84, v84, v216, -v183
	v_fma_f32 v85, v85, v216, v234
	v_mul_f32_e32 v183, v87, v219
	v_mul_f32_e32 v234, v86, v219
	v_fma_f32 v86, v86, v218, -v183
	v_fma_f32 v87, v87, v218, v234
	v_mul_f32_e32 v183, v81, v221
	v_mul_f32_e32 v234, v80, v221
	v_fma_f32 v80, v80, v220, -v183
	v_fma_f32 v81, v81, v220, v234
	v_mul_f32_e32 v183, v83, v223
	v_mul_f32_e32 v234, v82, v223
	v_fma_f32 v82, v82, v222, -v183
	v_fma_f32 v83, v83, v222, v234
	s_mov_b64 exec, s[96:97]
	v_mul_f32_e32 v84, v169, v84
	v_mul_f32_e32 v85, v169, v85
	v_mul_f32_e32 v86, v169, v86
	v_mul_f32_e32 v87, v169, v87
	v_mul_f32_e32 v80, v169, v80
	v_mul_f32_e32 v81, v169, v81
	v_mul_f32_e32 v82, v169, v82
	v_mul_f32_e32 v83, v169, v83
	v_cvt_pk_bf16_f32 v188, v84, v85
	v_cvt_pk_bf16_f32 v189, v86, v87
	v_cvt_pk_bf16_f32 v190, v80, v81
	v_cvt_pk_bf16_f32 v191, v82, v83
	global_store_dwordx4 v181, v[188:191], s[62:63] offset:256
	s_add_u32 s98, s44, 0x2800
	s_addc_u32 s99, s45, 0
	s_mov_b64 exec, s[68:69]
	global_load_dwordx4 v[216:219], v182, s[98:99]
	global_load_dwordx4 v[220:223], v182, s[98:99] offset:16
	s_mov_b64 exec, s[96:97]
	s_add_u32 s62, s12, 0x90000
	s_addc_u32 s63, s13, 0
	s_waitcnt vmcnt(12)
	s_mov_b64 exec, s[68:69]
	v_mul_f32_e32 v183, v77, v227
	v_mul_f32_e32 v234, v76, v227
	v_fma_f32 v76, v76, v226, -v183
	v_fma_f32 v77, v77, v226, v234
	v_mul_f32_e32 v183, v79, v229
	v_mul_f32_e32 v234, v78, v229
	v_fma_f32 v78, v78, v228, -v183
	v_fma_f32 v79, v79, v228, v234
	v_mul_f32_e32 v183, v73, v231
	v_mul_f32_e32 v234, v72, v231
	v_fma_f32 v72, v72, v230, -v183
	v_fma_f32 v73, v73, v230, v234
	v_mul_f32_e32 v183, v75, v233
	v_mul_f32_e32 v234, v74, v233
	v_fma_f32 v74, v74, v232, -v183
	v_fma_f32 v75, v75, v232, v234
	s_mov_b64 exec, s[96:97]
	v_mul_f32_e32 v76, v169, v76
	v_mul_f32_e32 v77, v169, v77
	v_mul_f32_e32 v78, v169, v78
	v_mul_f32_e32 v79, v169, v79
	v_mul_f32_e32 v72, v169, v72
	v_mul_f32_e32 v73, v169, v73
	v_mul_f32_e32 v74, v169, v74
	v_mul_f32_e32 v75, v169, v75
	v_cvt_pk_bf16_f32 v184, v76, v77
	v_cvt_pk_bf16_f32 v185, v78, v79
	v_cvt_pk_bf16_f32 v186, v72, v73
	v_cvt_pk_bf16_f32 v187, v74, v75
	global_store_dwordx4 v181, v[184:187], s[62:63] offset:0
	s_mov_b64 exec, s[68:69]
	v_mul_f32_e32 v183, v69, v227
	v_mul_f32_e32 v234, v68, v227
	v_fma_f32 v68, v68, v226, -v183
	v_fma_f32 v69, v69, v226, v234
	v_mul_f32_e32 v183, v71, v229
	v_mul_f32_e32 v234, v70, v229
	v_fma_f32 v70, v70, v228, -v183
	v_fma_f32 v71, v71, v228, v234
	v_mul_f32_e32 v183, v65, v231
	v_mul_f32_e32 v234, v64, v231
	v_fma_f32 v64, v64, v230, -v183
	v_fma_f32 v65, v65, v230, v234
	v_mul_f32_e32 v183, v67, v233
	v_mul_f32_e32 v234, v66, v233
	v_fma_f32 v66, v66, v232, -v183
	v_fma_f32 v67, v67, v232, v234
	s_mov_b64 exec, s[96:97]
	v_mul_f32_e32 v68, v169, v68
	v_mul_f32_e32 v69, v169, v69
	v_mul_f32_e32 v70, v169, v70
	v_mul_f32_e32 v71, v169, v71
	v_mul_f32_e32 v64, v169, v64
	v_mul_f32_e32 v65, v169, v65
	v_mul_f32_e32 v66, v169, v66
	v_mul_f32_e32 v67, v169, v67
	v_cvt_pk_bf16_f32 v188, v68, v69
	v_cvt_pk_bf16_f32 v189, v70, v71
	v_cvt_pk_bf16_f32 v190, v64, v65
	v_cvt_pk_bf16_f32 v191, v66, v67
	global_store_dwordx4 v181, v[188:191], s[62:63] offset:256
	s_add_u32 s98, s44, 0x2c00
	s_addc_u32 s99, s45, 0
	s_mov_b64 exec, s[68:69]
	global_load_dwordx4 v[226:229], v182, s[98:99]
	global_load_dwordx4 v[230:233], v182, s[98:99] offset:16
	s_mov_b64 exec, s[96:97]
	s_add_u32 s62, s12, 0x180000
	s_addc_u32 s63, s13, 0
	s_waitcnt vmcnt(12)
	s_mov_b64 exec, s[68:69]
	v_mul_f32_e32 v183, v61, v201
	v_mul_f32_e32 v234, v60, v201
	v_fma_f32 v60, v60, v200, -v183
	v_fma_f32 v61, v61, v200, v234
	v_mul_f32_e32 v183, v63, v203
	v_mul_f32_e32 v234, v62, v203
	v_fma_f32 v62, v62, v202, -v183
	v_fma_f32 v63, v63, v202, v234
	v_mul_f32_e32 v183, v57, v205
	v_mul_f32_e32 v234, v56, v205
	v_fma_f32 v56, v56, v204, -v183
	v_fma_f32 v57, v57, v204, v234
	v_mul_f32_e32 v183, v59, v207
	v_mul_f32_e32 v234, v58, v207
	v_fma_f32 v58, v58, v206, -v183
	v_fma_f32 v59, v59, v206, v234
	s_mov_b64 exec, s[96:97]
	v_mul_f32_e32 v60, v169, v60
	v_mul_f32_e32 v61, v169, v61
	v_mul_f32_e32 v62, v169, v62
	v_mul_f32_e32 v63, v169, v63
	v_mul_f32_e32 v56, v169, v56
	v_mul_f32_e32 v57, v169, v57
	v_mul_f32_e32 v58, v169, v58
	v_mul_f32_e32 v59, v169, v59
	v_cvt_pk_bf16_f32 v184, v60, v61
	v_cvt_pk_bf16_f32 v185, v62, v63
	v_cvt_pk_bf16_f32 v186, v56, v57
	v_cvt_pk_bf16_f32 v187, v58, v59
	global_store_dwordx4 v181, v[184:187], s[62:63] offset:0
	s_mov_b64 exec, s[68:69]
	v_mul_f32_e32 v183, v53, v201
	v_mul_f32_e32 v234, v52, v201
	v_fma_f32 v52, v52, v200, -v183
	v_fma_f32 v53, v53, v200, v234
	v_mul_f32_e32 v183, v55, v203
	v_mul_f32_e32 v234, v54, v203
	v_fma_f32 v54, v54, v202, -v183
	v_fma_f32 v55, v55, v202, v234
	v_mul_f32_e32 v183, v49, v205
	v_mul_f32_e32 v234, v48, v205
	v_fma_f32 v48, v48, v204, -v183
	v_fma_f32 v49, v49, v204, v234
	v_mul_f32_e32 v183, v51, v207
	v_mul_f32_e32 v234, v50, v207
	v_fma_f32 v50, v50, v206, -v183
	v_fma_f32 v51, v51, v206, v234
	s_mov_b64 exec, s[96:97]
	v_mul_f32_e32 v52, v169, v52
	v_mul_f32_e32 v53, v169, v53
	v_mul_f32_e32 v54, v169, v54
	v_mul_f32_e32 v55, v169, v55
	v_mul_f32_e32 v48, v169, v48
	v_mul_f32_e32 v49, v169, v49
	v_mul_f32_e32 v50, v169, v50
	v_mul_f32_e32 v51, v169, v51
	v_cvt_pk_bf16_f32 v188, v52, v53
	v_cvt_pk_bf16_f32 v189, v54, v55
	v_cvt_pk_bf16_f32 v190, v48, v49
	v_cvt_pk_bf16_f32 v191, v50, v51
	global_store_dwordx4 v181, v[188:191], s[62:63] offset:256
	s_add_u32 s62, s12, 0x1b0000
	s_addc_u32 s63, s13, 0
	s_waitcnt vmcnt(10)
	s_mov_b64 exec, s[68:69]
	v_mul_f32_e32 v183, v45, v209
	v_mul_f32_e32 v234, v44, v209
	v_fma_f32 v44, v44, v208, -v183
	v_fma_f32 v45, v45, v208, v234
	v_mul_f32_e32 v183, v47, v211
	v_mul_f32_e32 v234, v46, v211
	v_fma_f32 v46, v46, v210, -v183
	v_fma_f32 v47, v47, v210, v234
	v_mul_f32_e32 v183, v41, v213
	v_mul_f32_e32 v234, v40, v213
	v_fma_f32 v40, v40, v212, -v183
	v_fma_f32 v41, v41, v212, v234
	v_mul_f32_e32 v183, v43, v215
	v_mul_f32_e32 v234, v42, v215
	v_fma_f32 v42, v42, v214, -v183
	v_fma_f32 v43, v43, v214, v234
	s_mov_b64 exec, s[96:97]
	v_mul_f32_e32 v44, v169, v44
	v_mul_f32_e32 v45, v169, v45
	v_mul_f32_e32 v46, v169, v46
	v_mul_f32_e32 v47, v169, v47
	v_mul_f32_e32 v40, v169, v40
	v_mul_f32_e32 v41, v169, v41
	v_mul_f32_e32 v42, v169, v42
	v_mul_f32_e32 v43, v169, v43
	v_cvt_pk_bf16_f32 v184, v44, v45
	v_cvt_pk_bf16_f32 v185, v46, v47
	v_cvt_pk_bf16_f32 v186, v40, v41
	v_cvt_pk_bf16_f32 v187, v42, v43
	global_store_dwordx4 v181, v[184:187], s[62:63] offset:0
	s_mov_b64 exec, s[68:69]
	v_mul_f32_e32 v183, v37, v209
	v_mul_f32_e32 v234, v36, v209
	v_fma_f32 v36, v36, v208, -v183
	v_fma_f32 v37, v37, v208, v234
	v_mul_f32_e32 v183, v39, v211
	v_mul_f32_e32 v234, v38, v211
	v_fma_f32 v38, v38, v210, -v183
	v_fma_f32 v39, v39, v210, v234
	v_mul_f32_e32 v183, v33, v213
	v_mul_f32_e32 v234, v32, v213
	v_fma_f32 v32, v32, v212, -v183
	v_fma_f32 v33, v33, v212, v234
	v_mul_f32_e32 v183, v35, v215
	v_mul_f32_e32 v234, v34, v215
	v_fma_f32 v34, v34, v214, -v183
	v_fma_f32 v35, v35, v214, v234
	s_mov_b64 exec, s[96:97]
	v_mul_f32_e32 v36, v169, v36
	v_mul_f32_e32 v37, v169, v37
	v_mul_f32_e32 v38, v169, v38
	v_mul_f32_e32 v39, v169, v39
	v_mul_f32_e32 v32, v169, v32
	v_mul_f32_e32 v33, v169, v33
	v_mul_f32_e32 v34, v169, v34
	v_mul_f32_e32 v35, v169, v35
	v_cvt_pk_bf16_f32 v188, v36, v37
	v_cvt_pk_bf16_f32 v189, v38, v39
	v_cvt_pk_bf16_f32 v190, v32, v33
	v_cvt_pk_bf16_f32 v191, v34, v35
	global_store_dwordx4 v181, v[188:191], s[62:63] offset:256
	s_add_u32 s62, s12, 0x1e0000
	s_addc_u32 s63, s13, 0
	s_waitcnt vmcnt(8)
	s_mov_b64 exec, s[68:69]
	v_mul_f32_e32 v183, v29, v217
	v_mul_f32_e32 v234, v28, v217
	v_fma_f32 v28, v28, v216, -v183
	v_fma_f32 v29, v29, v216, v234
	v_mul_f32_e32 v183, v31, v219
	v_mul_f32_e32 v234, v30, v219
	v_fma_f32 v30, v30, v218, -v183
	v_fma_f32 v31, v31, v218, v234
	v_mul_f32_e32 v183, v25, v221
	v_mul_f32_e32 v234, v24, v221
	v_fma_f32 v24, v24, v220, -v183
	v_fma_f32 v25, v25, v220, v234
	v_mul_f32_e32 v183, v27, v223
	v_mul_f32_e32 v234, v26, v223
	v_fma_f32 v26, v26, v222, -v183
	v_fma_f32 v27, v27, v222, v234
	s_mov_b64 exec, s[96:97]
	v_mul_f32_e32 v28, v169, v28
	v_mul_f32_e32 v29, v169, v29
	v_mul_f32_e32 v30, v169, v30
	v_mul_f32_e32 v31, v169, v31
	v_mul_f32_e32 v24, v169, v24
	v_mul_f32_e32 v25, v169, v25
	v_mul_f32_e32 v26, v169, v26
	v_mul_f32_e32 v27, v169, v27
	v_cvt_pk_bf16_f32 v184, v28, v29
	v_cvt_pk_bf16_f32 v185, v30, v31
	v_cvt_pk_bf16_f32 v186, v24, v25
	v_cvt_pk_bf16_f32 v187, v26, v27
	global_store_dwordx4 v181, v[184:187], s[62:63] offset:0
	s_mov_b64 exec, s[68:69]
	v_mul_f32_e32 v183, v21, v217
	v_mul_f32_e32 v234, v20, v217
	v_fma_f32 v20, v20, v216, -v183
	v_fma_f32 v21, v21, v216, v234
	v_mul_f32_e32 v183, v23, v219
	v_mul_f32_e32 v234, v22, v219
	v_fma_f32 v22, v22, v218, -v183
	v_fma_f32 v23, v23, v218, v234
	v_mul_f32_e32 v183, v17, v221
	v_mul_f32_e32 v234, v16, v221
	v_fma_f32 v16, v16, v220, -v183
	v_fma_f32 v17, v17, v220, v234
	v_mul_f32_e32 v183, v19, v223
	v_mul_f32_e32 v234, v18, v223
	v_fma_f32 v18, v18, v222, -v183
	v_fma_f32 v19, v19, v222, v234
	s_mov_b64 exec, s[96:97]
	v_mul_f32_e32 v20, v169, v20
	v_mul_f32_e32 v21, v169, v21
	v_mul_f32_e32 v22, v169, v22
	v_mul_f32_e32 v23, v169, v23
	v_mul_f32_e32 v16, v169, v16
	v_mul_f32_e32 v17, v169, v17
	v_mul_f32_e32 v18, v169, v18
	v_mul_f32_e32 v19, v169, v19
	v_cvt_pk_bf16_f32 v188, v20, v21
	v_cvt_pk_bf16_f32 v189, v22, v23
	v_cvt_pk_bf16_f32 v190, v16, v17
	v_cvt_pk_bf16_f32 v191, v18, v19
	global_store_dwordx4 v181, v[188:191], s[62:63] offset:256
	s_add_u32 s62, s12, 0x210000
	s_addc_u32 s63, s13, 0
	s_waitcnt vmcnt(6)
	s_mov_b64 exec, s[68:69]
	v_mul_f32_e32 v183, v13, v227
	v_mul_f32_e32 v234, v12, v227
	v_fma_f32 v12, v12, v226, -v183
	v_fma_f32 v13, v13, v226, v234
	v_mul_f32_e32 v183, v15, v229
	v_mul_f32_e32 v234, v14, v229
	v_fma_f32 v14, v14, v228, -v183
	v_fma_f32 v15, v15, v228, v234
	v_mul_f32_e32 v183, v9, v231
	v_mul_f32_e32 v234, v8, v231
	v_fma_f32 v8, v8, v230, -v183
	v_fma_f32 v9, v9, v230, v234
	v_mul_f32_e32 v183, v11, v233
	v_mul_f32_e32 v234, v10, v233
	v_fma_f32 v10, v10, v232, -v183
	v_fma_f32 v11, v11, v232, v234
	s_mov_b64 exec, s[96:97]
	v_mul_f32_e32 v12, v169, v12
	v_mul_f32_e32 v13, v169, v13
	v_mul_f32_e32 v14, v169, v14
	v_mul_f32_e32 v15, v169, v15
	v_mul_f32_e32 v8, v169, v8
	v_mul_f32_e32 v9, v169, v9
	v_mul_f32_e32 v10, v169, v10
	v_mul_f32_e32 v11, v169, v11
	v_cvt_pk_bf16_f32 v184, v12, v13
	v_cvt_pk_bf16_f32 v185, v14, v15
	v_cvt_pk_bf16_f32 v186, v8, v9
	v_cvt_pk_bf16_f32 v187, v10, v11
	global_store_dwordx4 v181, v[184:187], s[62:63] offset:0
	s_mov_b64 exec, s[68:69]
	v_mul_f32_e32 v183, v5, v227
	v_mul_f32_e32 v234, v4, v227
	v_fma_f32 v4, v4, v226, -v183
	v_fma_f32 v5, v5, v226, v234
	v_mul_f32_e32 v183, v7, v229
	v_mul_f32_e32 v234, v6, v229
	v_fma_f32 v6, v6, v228, -v183
	v_fma_f32 v7, v7, v228, v234
	v_mul_f32_e32 v183, v1, v231
	v_mul_f32_e32 v234, v0, v231
	v_fma_f32 v0, v0, v230, -v183
	v_fma_f32 v1, v1, v230, v234
	v_mul_f32_e32 v183, v3, v233
	v_mul_f32_e32 v234, v2, v233
	v_fma_f32 v2, v2, v232, -v183
	v_fma_f32 v3, v3, v232, v234
	s_mov_b64 exec, s[96:97]
	v_mul_f32_e32 v4, v169, v4
	v_mul_f32_e32 v5, v169, v5
	v_mul_f32_e32 v6, v169, v6
	v_mul_f32_e32 v7, v169, v7
	v_mul_f32_e32 v0, v169, v0
	v_mul_f32_e32 v1, v169, v1
	v_mul_f32_e32 v2, v169, v2
	v_mul_f32_e32 v3, v169, v3
	v_cvt_pk_bf16_f32 v188, v4, v5
	v_cvt_pk_bf16_f32 v189, v6, v7
	v_cvt_pk_bf16_f32 v190, v0, v1
	v_cvt_pk_bf16_f32 v191, v2, v3
	global_store_dwordx4 v181, v[188:191], s[62:63] offset:256
	s_branch .Lep_fast_done
.Lep_kind3n:
	s_mov_b64 s[62:63], s[12:13]
	v_mul_f32_e32 v124, v169, v124
	v_mul_f32_e32 v125, v169, v125
	v_mul_f32_e32 v126, v169, v126
	v_mul_f32_e32 v127, v169, v127
	v_mul_f32_e32 v120, v169, v120
	v_mul_f32_e32 v121, v169, v121
	v_mul_f32_e32 v122, v169, v122
	v_mul_f32_e32 v123, v169, v123
	v_cvt_pk_bf16_f32 v184, v124, v125
	v_cvt_pk_bf16_f32 v185, v126, v127
	v_cvt_pk_bf16_f32 v186, v120, v121
	v_cvt_pk_bf16_f32 v187, v122, v123
	global_store_dwordx4 v181, v[184:187], s[62:63] offset:0
	v_mul_f32_e32 v116, v169, v116
	v_mul_f32_e32 v117, v169, v117
	v_mul_f32_e32 v118, v169, v118
	v_mul_f32_e32 v119, v169, v119
	v_mul_f32_e32 v112, v169, v112
	v_mul_f32_e32 v113, v169, v113
	v_mul_f32_e32 v114, v169, v114
	v_mul_f32_e32 v115, v169, v115
	v_cvt_pk_bf16_f32 v188, v116, v117
	v_cvt_pk_bf16_f32 v189, v118, v119
	v_cvt_pk_bf16_f32 v190, v112, v113
	v_cvt_pk_bf16_f32 v191, v114, v115
	global_store_dwordx4 v181, v[188:191], s[62:63] offset:256
	s_add_u32 s62, s12, 0x30000
	s_addc_u32 s63, s13, 0
	v_mul_f32_e32 v108, v169, v108
	v_mul_f32_e32 v109, v169, v109
	v_mul_f32_e32 v110, v169, v110
	v_mul_f32_e32 v111, v169, v111
	v_mul_f32_e32 v104, v169, v104
	v_mul_f32_e32 v105, v169, v105
	v_mul_f32_e32 v106, v169, v106
	v_mul_f32_e32 v107, v169, v107
	v_cvt_pk_bf16_f32 v184, v108, v109
	v_cvt_pk_bf16_f32 v185, v110, v111
	v_cvt_pk_bf16_f32 v186, v104, v105
	v_cvt_pk_bf16_f32 v187, v106, v107
	global_store_dwordx4 v181, v[184:187], s[62:63] offset:0
	v_mul_f32_e32 v100, v169, v100
	v_mul_f32_e32 v101, v169, v101
	v_mul_f32_e32 v102, v169, v102
	v_mul_f32_e32 v103, v169, v103
	v_mul_f32_e32 v96, v169, v96
	v_mul_f32_e32 v97, v169, v97
	v_mul_f32_e32 v98, v169, v98
	v_mul_f32_e32 v99, v169, v99
	v_cvt_pk_bf16_f32 v188, v100, v101
	v_cvt_pk_bf16_f32 v189, v102, v103
	v_cvt_pk_bf16_f32 v190, v96, v97
	v_cvt_pk_bf16_f32 v191, v98, v99
	global_store_dwordx4 v181, v[188:191], s[62:63] offset:256
	s_add_u32 s62, s12, 0x60000
	s_addc_u32 s63, s13, 0
	v_mul_f32_e32 v92, v169, v92
	v_mul_f32_e32 v93, v169, v93
	v_mul_f32_e32 v94, v169, v94
	v_mul_f32_e32 v95, v169, v95
	v_mul_f32_e32 v88, v169, v88
	v_mul_f32_e32 v89, v169, v89
	v_mul_f32_e32 v90, v169, v90
	v_mul_f32_e32 v91, v169, v91
	v_cvt_pk_bf16_f32 v184, v92, v93
	v_cvt_pk_bf16_f32 v185, v94, v95
	v_cvt_pk_bf16_f32 v186, v88, v89
	v_cvt_pk_bf16_f32 v187, v90, v91
	global_store_dwordx4 v181, v[184:187], s[62:63] offset:0
	v_mul_f32_e32 v84, v169, v84
	v_mul_f32_e32 v85, v169, v85
	v_mul_f32_e32 v86, v169, v86
	v_mul_f32_e32 v87, v169, v87
	v_mul_f32_e32 v80, v169, v80
	v_mul_f32_e32 v81, v169, v81
	v_mul_f32_e32 v82, v169, v82
	v_mul_f32_e32 v83, v169, v83
	v_cvt_pk_bf16_f32 v188, v84, v85
	v_cvt_pk_bf16_f32 v189, v86, v87
	v_cvt_pk_bf16_f32 v190, v80, v81
	v_cvt_pk_bf16_f32 v191, v82, v83
	global_store_dwordx4 v181, v[188:191], s[62:63] offset:256
	s_add_u32 s62, s12, 0x90000
	s_addc_u32 s63, s13, 0
	v_mul_f32_e32 v76, v169, v76
	v_mul_f32_e32 v77, v169, v77
	v_mul_f32_e32 v78, v169, v78
	v_mul_f32_e32 v79, v169, v79
	v_mul_f32_e32 v72, v169, v72
	v_mul_f32_e32 v73, v169, v73
	v_mul_f32_e32 v74, v169, v74
	v_mul_f32_e32 v75, v169, v75
	v_cvt_pk_bf16_f32 v184, v76, v77
	v_cvt_pk_bf16_f32 v185, v78, v79
	v_cvt_pk_bf16_f32 v186, v72, v73
	v_cvt_pk_bf16_f32 v187, v74, v75
	global_store_dwordx4 v181, v[184:187], s[62:63] offset:0
	v_mul_f32_e32 v68, v169, v68
	v_mul_f32_e32 v69, v169, v69
	v_mul_f32_e32 v70, v169, v70
	v_mul_f32_e32 v71, v169, v71
	v_mul_f32_e32 v64, v169, v64
	v_mul_f32_e32 v65, v169, v65
	v_mul_f32_e32 v66, v169, v66
	v_mul_f32_e32 v67, v169, v67
	v_cvt_pk_bf16_f32 v188, v68, v69
	v_cvt_pk_bf16_f32 v189, v70, v71
	v_cvt_pk_bf16_f32 v190, v64, v65
	v_cvt_pk_bf16_f32 v191, v66, v67
	global_store_dwordx4 v181, v[188:191], s[62:63] offset:256
	s_add_u32 s62, s12, 0x180000
	s_addc_u32 s63, s13, 0
	v_mul_f32_e32 v60, v169, v60
	v_mul_f32_e32 v61, v169, v61
	v_mul_f32_e32 v62, v169, v62
	v_mul_f32_e32 v63, v169, v63
	v_mul_f32_e32 v56, v169, v56
	v_mul_f32_e32 v57, v169, v57
	v_mul_f32_e32 v58, v169, v58
	v_mul_f32_e32 v59, v169, v59
	v_cvt_pk_bf16_f32 v184, v60, v61
	v_cvt_pk_bf16_f32 v185, v62, v63
	v_cvt_pk_bf16_f32 v186, v56, v57
	v_cvt_pk_bf16_f32 v187, v58, v59
	global_store_dwordx4 v181, v[184:187], s[62:63] offset:0
	v_mul_f32_e32 v52, v169, v52
	v_mul_f32_e32 v53, v169, v53
	v_mul_f32_e32 v54, v169, v54
	v_mul_f32_e32 v55, v169, v55
	v_mul_f32_e32 v48, v169, v48
	v_mul_f32_e32 v49, v169, v49
	v_mul_f32_e32 v50, v169, v50
	v_mul_f32_e32 v51, v169, v51
	v_cvt_pk_bf16_f32 v188, v52, v53
	v_cvt_pk_bf16_f32 v189, v54, v55
	v_cvt_pk_bf16_f32 v190, v48, v49
	v_cvt_pk_bf16_f32 v191, v50, v51
	global_store_dwordx4 v181, v[188:191], s[62:63] offset:256
	s_add_u32 s62, s12, 0x1b0000
	s_addc_u32 s63, s13, 0
	v_mul_f32_e32 v44, v169, v44
	v_mul_f32_e32 v45, v169, v45
	v_mul_f32_e32 v46, v169, v46
	v_mul_f32_e32 v47, v169, v47
	v_mul_f32_e32 v40, v169, v40
	v_mul_f32_e32 v41, v169, v41
	v_mul_f32_e32 v42, v169, v42
	v_mul_f32_e32 v43, v169, v43
	v_cvt_pk_bf16_f32 v184, v44, v45
	v_cvt_pk_bf16_f32 v185, v46, v47
	v_cvt_pk_bf16_f32 v186, v40, v41
	v_cvt_pk_bf16_f32 v187, v42, v43
	global_store_dwordx4 v181, v[184:187], s[62:63] offset:0
	v_mul_f32_e32 v36, v169, v36
	v_mul_f32_e32 v37, v169, v37
	v_mul_f32_e32 v38, v169, v38
	v_mul_f32_e32 v39, v169, v39
	v_mul_f32_e32 v32, v169, v32
	v_mul_f32_e32 v33, v169, v33
	v_mul_f32_e32 v34, v169, v34
	v_mul_f32_e32 v35, v169, v35
	v_cvt_pk_bf16_f32 v188, v36, v37
	v_cvt_pk_bf16_f32 v189, v38, v39
	v_cvt_pk_bf16_f32 v190, v32, v33
	v_cvt_pk_bf16_f32 v191, v34, v35
	global_store_dwordx4 v181, v[188:191], s[62:63] offset:256
	s_add_u32 s62, s12, 0x1e0000
	s_addc_u32 s63, s13, 0
	v_mul_f32_e32 v28, v169, v28
	v_mul_f32_e32 v29, v169, v29
	v_mul_f32_e32 v30, v169, v30
	v_mul_f32_e32 v31, v169, v31
	v_mul_f32_e32 v24, v169, v24
	v_mul_f32_e32 v25, v169, v25
	v_mul_f32_e32 v26, v169, v26
	v_mul_f32_e32 v27, v169, v27
	v_cvt_pk_bf16_f32 v184, v28, v29
	v_cvt_pk_bf16_f32 v185, v30, v31
	v_cvt_pk_bf16_f32 v186, v24, v25
	v_cvt_pk_bf16_f32 v187, v26, v27
	global_store_dwordx4 v181, v[184:187], s[62:63] offset:0
	v_mul_f32_e32 v20, v169, v20
	v_mul_f32_e32 v21, v169, v21
	v_mul_f32_e32 v22, v169, v22
	v_mul_f32_e32 v23, v169, v23
	v_mul_f32_e32 v16, v169, v16
	v_mul_f32_e32 v17, v169, v17
	v_mul_f32_e32 v18, v169, v18
	v_mul_f32_e32 v19, v169, v19
	v_cvt_pk_bf16_f32 v188, v20, v21
	v_cvt_pk_bf16_f32 v189, v22, v23
	v_cvt_pk_bf16_f32 v190, v16, v17
	v_cvt_pk_bf16_f32 v191, v18, v19
	global_store_dwordx4 v181, v[188:191], s[62:63] offset:256
	s_add_u32 s62, s12, 0x210000
	s_addc_u32 s63, s13, 0
	v_mul_f32_e32 v12, v169, v12
	v_mul_f32_e32 v13, v169, v13
	v_mul_f32_e32 v14, v169, v14
	v_mul_f32_e32 v15, v169, v15
	v_mul_f32_e32 v8, v169, v8
	v_mul_f32_e32 v9, v169, v9
	v_mul_f32_e32 v10, v169, v10
	v_mul_f32_e32 v11, v169, v11
	v_cvt_pk_bf16_f32 v184, v12, v13
	v_cvt_pk_bf16_f32 v185, v14, v15
	v_cvt_pk_bf16_f32 v186, v8, v9
	v_cvt_pk_bf16_f32 v187, v10, v11
	global_store_dwordx4 v181, v[184:187], s[62:63] offset:0
	v_mul_f32_e32 v4, v169, v4
	v_mul_f32_e32 v5, v169, v5
	v_mul_f32_e32 v6, v169, v6
	v_mul_f32_e32 v7, v169, v7
	v_mul_f32_e32 v0, v169, v0
	v_mul_f32_e32 v1, v169, v1
	v_mul_f32_e32 v2, v169, v2
	v_mul_f32_e32 v3, v169, v3
	v_cvt_pk_bf16_f32 v188, v4, v5
	v_cvt_pk_bf16_f32 v189, v6, v7
	v_cvt_pk_bf16_f32 v190, v0, v1
	v_cvt_pk_bf16_f32 v191, v2, v3
	global_store_dwordx4 v181, v[188:191], s[62:63] offset:256
	s_branch .Lep_fast_done
.Lep_kind4:
	s_mov_b64 s[96:97], exec
	s_and_b64 s[68:69], s[48:49], s[6:7]
	s_cbranch_scc0 .Lep_kind4n
	v_and_b32_e32 v182, 0x7ff, v180
	v_lshlrev_b32_e32 v182, 6, v182
	v_lshl_add_u32 v182, v164, 2, v182
	v_and_b32_e32 v181, 0x7ff, v180
	v_lshlrev_b32_e32 v181, 8, v181
	v_lshl_add_u32 v181, v146, 1, v181
	s_lshr_b32 s61, s60, 3
	s_add_i32 s61, s61, 8
	s_lshl_b32 s61, s61, 3
	s_and_b32 s95, s16, 3
	s_lshl_b32 s95, s95, 1
	s_add_i32 s61, s61, s95
	s_lshl_b32 s61, s61, 19
	s_add_u32 s66, s14, s61
	s_addc_u32 s67, s15, 0
	s_mov_b64 s[98:99], s[44:45]
	s_mov_b64 exec, s[68:69]
	global_load_dwordx4 v[200:203], v182, s[98:99]
	global_load_dwordx4 v[204:207], v182, s[98:99] offset:16
	s_mov_b64 exec, s[96:97]
	s_add_u32 s98, s44, 0x400
	s_addc_u32 s99, s45, 0
	s_mov_b64 exec, s[68:69]
	global_load_dwordx4 v[208:211], v182, s[98:99]
	global_load_dwordx4 v[212:215], v182, s[98:99] offset:16
	s_mov_b64 exec, s[96:97]
	s_add_u32 s98, s44, 0x800
	s_addc_u32 s99, s45, 0
	s_mov_b64 exec, s[68:69]
	global_load_dwordx4 v[216:219], v182, s[98:99]
	global_load_dwordx4 v[220:223], v182, s[98:99] offset:16
	s_mov_b64 exec, s[96:97]
	s_add_u32 s98, s44, 0xc00
	s_addc_u32 s99, s45, 0
	s_mov_b64 exec, s[68:69]
	global_load_dwordx4 v[226:229], v182, s[98:99]
	global_load_dwordx4 v[230:233], v182, s[98:99] offset:16
	s_mov_b64 exec, s[96:97]
	s_add_u32 s62, s66, 0x0
	s_addc_u32 s63, s67, 0
	s_add_u32 s64, s66, 0x80000
	s_addc_u32 s65, s67, 0
	s_waitcnt vmcnt(6)
	s_mov_b64 exec, s[68:69]
	v_mul_f32_e32 v183, v125, v201
	v_mul_f32_e32 v234, v124, v201
	v_fma_f32 v124, v124, v200, -v183
	v_fma_f32 v125, v125, v200, v234
	v_mul_f32_e32 v183, v127, v203
	v_mul_f32_e32 v234, v126, v203
	v_fma_f32 v126, v126, v202, -v183
	v_fma_f32 v127, v127, v202, v234
	v_mul_f32_e32 v183, v121, v205
	v_mul_f32_e32 v234, v120, v205
	v_fma_f32 v120, v120, v204, -v183
	v_fma_f32 v121, v121, v204, v234
	v_mul_f32_e32 v183, v123, v207
	v_mul_f32_e32 v234, v122, v207
	v_fma_f32 v122, v122, v206, -v183
	v_fma_f32 v123, v123, v206, v234
	s_mov_b64 exec, s[96:97]
	v_cvt_pk_bf16_f32 v184, v124, v125
	v_cvt_pk_bf16_f32 v185, v126, v127
	v_cvt_pk_bf16_f32 v186, v120, v121
	v_cvt_pk_bf16_f32 v187, v122, v123
	global_store_dwordx4 v181, v[184:187], s[62:63]
	s_mov_b64 exec, s[68:69]
	v_mul_f32_e32 v183, v117, v201
	v_mul_f32_e32 v234, v116, v201
	v_fma_f32 v116, v116, v200, -v183
	v_fma_f32 v117, v117, v200, v234
	v_mul_f32_e32 v183, v119, v203
	v_mul_f32_e32 v234, v118, v203
	v_fma_f32 v118, v118, v202, -v183
	v_fma_f32 v119, v119, v202, v234
	v_mul_f32_e32 v183, v113, v205
	v_mul_f32_e32 v234, v112, v205
	v_fma_f32 v112, v112, v204, -v183
	v_fma_f32 v113, v113, v204, v234
	v_mul_f32_e32 v183, v115, v207
	v_mul_f32_e32 v234, v114, v207
	v_fma_f32 v114, v114, v206, -v183
	v_fma_f32 v115, v115, v206, v234
	s_mov_b64 exec, s[96:97]
	v_cvt_pk_bf16_f32 v188, v116, v117
	v_cvt_pk_bf16_f32 v189, v118, v119
	v_cvt_pk_bf16_f32 v190, v112, v113
	v_cvt_pk_bf16_f32 v191, v114, v115
	global_store_dwordx4 v181, v[188:191], s[64:65]
	s_add_u32 s98, s44, 0x2000
	s_addc_u32 s99, s45, 0
	s_mov_b64 exec, s[68:69]
	global_load_dwordx4 v[200:203], v182, s[98:99]
	global_load_dwordx4 v[204:207], v182, s[98:99] offset:16
	s_mov_b64 exec, s[96:97]
	s_add_u32 s62, s66, 0x1000
	s_addc_u32 s63, s67, 0
	s_add_u32 s64, s66, 0x81000
	s_addc_u32 s65, s67, 0
	s_waitcnt vmcnt(8)
	s_mov_b64 exec, s[68:69]
	v_mul_f32_e32 v183, v109, v209
	v_mul_f32_e32 v234, v108, v209
	v_fma_f32 v108, v108, v208, -v183
	v_fma_f32 v109, v109, v208, v234
	v_mul_f32_e32 v183, v111, v211
	v_mul_f32_e32 v234, v110, v211
	v_fma_f32 v110, v110, v210, -v183
	v_fma_f32 v111, v111, v210, v234
	v_mul_f32_e32 v183, v105, v213
	v_mul_f32_e32 v234, v104, v213
	v_fma_f32 v104, v104, v212, -v183
	v_fma_f32 v105, v105, v212, v234
	v_mul_f32_e32 v183, v107, v215
	v_mul_f32_e32 v234, v106, v215
	v_fma_f32 v106, v106, v214, -v183
	v_fma_f32 v107, v107, v214, v234
	s_mov_b64 exec, s[96:97]
	v_cvt_pk_bf16_f32 v184, v108, v109
	v_cvt_pk_bf16_f32 v185, v110, v111
	v_cvt_pk_bf16_f32 v186, v104, v105
	v_cvt_pk_bf16_f32 v187, v106, v107
	global_store_dwordx4 v181, v[184:187], s[62:63]
	s_mov_b64 exec, s[68:69]
	v_mul_f32_e32 v183, v101, v209
	v_mul_f32_e32 v234, v100, v209
	v_fma_f32 v100, v100, v208, -v183
	v_fma_f32 v101, v101, v208, v234
	v_mul_f32_e32 v183, v103, v211
	v_mul_f32_e32 v234, v102, v211
	v_fma_f32 v102, v102, v210, -v183
	v_fma_f32 v103, v103, v210, v234
	v_mul_f32_e32 v183, v97, v213
	v_mul_f32_e32 v234, v96, v213
	v_fma_f32 v96, v96, v212, -v183
	v_fma_f32 v97, v97, v212, v234
	v_mul_f32_e32 v183, v99, v215
	v_mul_f32_e32 v234, v98, v215
	v_fma_f32 v98, v98, v214, -v183
	v_fma_f32 v99, v99, v214, v234
	s_mov_b64 exec, s[96:97]
	v_cvt_pk_bf16_f32 v188, v100, v101
	v_cvt_pk_bf16_f32 v189, v102, v103
	v_cvt_pk_bf16_f32 v190, v96, v97
	v_cvt_pk_bf16_f32 v191, v98, v99
	global_store_dwordx4 v181, v[188:191], s[64:65]
	s_add_u32 s98, s44, 0x2400
	s_addc_u32 s99, s45, 0
	s_mov_b64 exec, s[68:69]
	global_load_dwordx4 v[208:211], v182, s[98:99]
	global_load_dwordx4 v[212:215], v182, s[98:99] offset:16
	s_mov_b64 exec, s[96:97]
	s_add_u32 s62, s66, 0x2000
	s_addc_u32 s63, s67, 0
	s_add_u32 s64, s66, 0x82000
	s_addc_u32 s65, s67, 0
	s_waitcnt vmcnt(10)
	s_mov_b64 exec, s[68:69]
	v_mul_f32_e32 v183, v93, v217
	v_mul_f32_e32 v234, v92, v217
	v_fma_f32 v92, v92, v216, -v183
	v_fma_f32 v93, v93, v216, v234
	v_mul_f32_e32 v183, v95, v219
	v_mul_f32_e32 v234, v94, v219
	v_fma_f32 v94, v94, v218, -v183
	v_fma_f32 v95, v95, v218, v234
	v_mul_f32_e32 v183, v89, v221
	v_mul_f32_e32 v234, v88, v221
	v_fma_f32 v88, v88, v220, -v183
	v_fma_f32 v89, v89, v220, v234
	v_mul_f32_e32 v183, v91, v223
	v_mul_f32_e32 v234, v90, v223
	v_fma_f32 v90, v90, v222, -v183
	v_fma_f32 v91, v91, v222, v234
	s_mov_b64 exec, s[96:97]
	v_cvt_pk_bf16_f32 v184, v92, v93
	v_cvt_pk_bf16_f32 v185, v94, v95
	v_cvt_pk_bf16_f32 v186, v88, v89
	v_cvt_pk_bf16_f32 v187, v90, v91
	global_store_dwordx4 v181, v[184:187], s[62:63]
	s_mov_b64 exec, s[68:69]
	v_mul_f32_e32 v183, v85, v217
	v_mul_f32_e32 v234, v84, v217
	v_fma_f32 v84, v84, v216, -v183
	v_fma_f32 v85, v85, v216, v234
	v_mul_f32_e32 v183, v87, v219
	v_mul_f32_e32 v234, v86, v219
	v_fma_f32 v86, v86, v218, -v183
	v_fma_f32 v87, v87, v218, v234
	v_mul_f32_e32 v183, v81, v221
	v_mul_f32_e32 v234, v80, v221
	v_fma_f32 v80, v80, v220, -v183
	v_fma_f32 v81, v81, v220, v234
	v_mul_f32_e32 v183, v83, v223
	v_mul_f32_e32 v234, v82, v223
	v_fma_f32 v82, v82, v222, -v183
	v_fma_f32 v83, v83, v222, v234
	s_mov_b64 exec, s[96:97]
	v_cvt_pk_bf16_f32 v188, v84, v85
	v_cvt_pk_bf16_f32 v189, v86, v87
	v_cvt_pk_bf16_f32 v190, v80, v81
	v_cvt_pk_bf16_f32 v191, v82, v83
	global_store_dwordx4 v181, v[188:191], s[64:65]
	s_add_u32 s98, s44, 0x2800
	s_addc_u32 s99, s45, 0
	s_mov_b64 exec, s[68:69]
	global_load_dwordx4 v[216:219], v182, s[98:99]
	global_load_dwordx4 v[220:223], v182, s[98:99] offset:16
	s_mov_b64 exec, s[96:97]
	s_add_u32 s62, s66, 0x3000
	s_addc_u32 s63, s67, 0
	s_add_u32 s64, s66, 0x83000
	s_addc_u32 s65, s67, 0
	s_waitcnt vmcnt(12)
	s_mov_b64 exec, s[68:69]
	v_mul_f32_e32 v183, v77, v227
	v_mul_f32_e32 v234, v76, v227
	v_fma_f32 v76, v76, v226, -v183
	v_fma_f32 v77, v77, v226, v234
	v_mul_f32_e32 v183, v79, v229
	v_mul_f32_e32 v234, v78, v229
	v_fma_f32 v78, v78, v228, -v183
	v_fma_f32 v79, v79, v228, v234
	v_mul_f32_e32 v183, v73, v231
	v_mul_f32_e32 v234, v72, v231
	v_fma_f32 v72, v72, v230, -v183
	v_fma_f32 v73, v73, v230, v234
	v_mul_f32_e32 v183, v75, v233
	v_mul_f32_e32 v234, v74, v233
	v_fma_f32 v74, v74, v232, -v183
	v_fma_f32 v75, v75, v232, v234
	s_mov_b64 exec, s[96:97]
	v_cvt_pk_bf16_f32 v184, v76, v77
	v_cvt_pk_bf16_f32 v185, v78, v79
	v_cvt_pk_bf16_f32 v186, v72, v73
	v_cvt_pk_bf16_f32 v187, v74, v75
	global_store_dwordx4 v181, v[184:187], s[62:63]
	s_mov_b64 exec, s[68:69]
	v_mul_f32_e32 v183, v69, v227
	v_mul_f32_e32 v234, v68, v227
	v_fma_f32 v68, v68, v226, -v183
	v_fma_f32 v69, v69, v226, v234
	v_mul_f32_e32 v183, v71, v229
	v_mul_f32_e32 v234, v70, v229
	v_fma_f32 v70, v70, v228, -v183
	v_fma_f32 v71, v71, v228, v234
	v_mul_f32_e32 v183, v65, v231
	v_mul_f32_e32 v234, v64, v231
	v_fma_f32 v64, v64, v230, -v183
	v_fma_f32 v65, v65, v230, v234
	v_mul_f32_e32 v183, v67, v233
	v_mul_f32_e32 v234, v66, v233
	v_fma_f32 v66, v66, v232, -v183
	v_fma_f32 v67, v67, v232, v234
	s_mov_b64 exec, s[96:97]
	v_cvt_pk_bf16_f32 v188, v68, v69
	v_cvt_pk_bf16_f32 v189, v70, v71
	v_cvt_pk_bf16_f32 v190, v64, v65
	v_cvt_pk_bf16_f32 v191, v66, v67
	global_store_dwordx4 v181, v[188:191], s[64:65]
	s_add_u32 s98, s44, 0x2c00
	s_addc_u32 s99, s45, 0
	s_mov_b64 exec, s[68:69]
	global_load_dwordx4 v[226:229], v182, s[98:99]
	global_load_dwordx4 v[230:233], v182, s[98:99] offset:16
	s_mov_b64 exec, s[96:97]
	s_add_u32 s62, s66, 0x8000
	s_addc_u32 s63, s67, 0
	s_add_u32 s64, s66, 0x88000
	s_addc_u32 s65, s67, 0
	s_waitcnt vmcnt(12)
	s_mov_b64 exec, s[68:69]
	v_mul_f32_e32 v183, v61, v201
	v_mul_f32_e32 v234, v60, v201
	v_fma_f32 v60, v60, v200, -v183
	v_fma_f32 v61, v61, v200, v234
	v_mul_f32_e32 v183, v63, v203
	v_mul_f32_e32 v234, v62, v203
	v_fma_f32 v62, v62, v202, -v183
	v_fma_f32 v63, v63, v202, v234
	v_mul_f32_e32 v183, v57, v205
	v_mul_f32_e32 v234, v56, v205
	v_fma_f32 v56, v56, v204, -v183
	v_fma_f32 v57, v57, v204, v234
	v_mul_f32_e32 v183, v59, v207
	v_mul_f32_e32 v234, v58, v207
	v_fma_f32 v58, v58, v206, -v183
	v_fma_f32 v59, v59, v206, v234
	s_mov_b64 exec, s[96:97]
	v_cvt_pk_bf16_f32 v184, v60, v61
	v_cvt_pk_bf16_f32 v185, v62, v63
	v_cvt_pk_bf16_f32 v186, v56, v57
	v_cvt_pk_bf16_f32 v187, v58, v59
	global_store_dwordx4 v181, v[184:187], s[62:63]
	s_mov_b64 exec, s[68:69]
	v_mul_f32_e32 v183, v53, v201
	v_mul_f32_e32 v234, v52, v201
	v_fma_f32 v52, v52, v200, -v183
	v_fma_f32 v53, v53, v200, v234
	v_mul_f32_e32 v183, v55, v203
	v_mul_f32_e32 v234, v54, v203
	v_fma_f32 v54, v54, v202, -v183
	v_fma_f32 v55, v55, v202, v234
	v_mul_f32_e32 v183, v49, v205
	v_mul_f32_e32 v234, v48, v205
	v_fma_f32 v48, v48, v204, -v183
	v_fma_f32 v49, v49, v204, v234
	v_mul_f32_e32 v183, v51, v207
	v_mul_f32_e32 v234, v50, v207
	v_fma_f32 v50, v50, v206, -v183
	v_fma_f32 v51, v51, v206, v234
	s_mov_b64 exec, s[96:97]
	v_cvt_pk_bf16_f32 v188, v52, v53
	v_cvt_pk_bf16_f32 v189, v54, v55
	v_cvt_pk_bf16_f32 v190, v48, v49
	v_cvt_pk_bf16_f32 v191, v50, v51
	global_store_dwordx4 v181, v[188:191], s[64:65]
	s_add_u32 s62, s66, 0x9000
	s_addc_u32 s63, s67, 0
	s_add_u32 s64, s66, 0x89000
	s_addc_u32 s65, s67, 0
	s_waitcnt vmcnt(10)
	s_mov_b64 exec, s[68:69]
	v_mul_f32_e32 v183, v45, v209
	v_mul_f32_e32 v234, v44, v209
	v_fma_f32 v44, v44, v208, -v183
	v_fma_f32 v45, v45, v208, v234
	v_mul_f32_e32 v183, v47, v211
	v_mul_f32_e32 v234, v46, v211
	v_fma_f32 v46, v46, v210, -v183
	v_fma_f32 v47, v47, v210, v234
	v_mul_f32_e32 v183, v41, v213
	v_mul_f32_e32 v234, v40, v213
	v_fma_f32 v40, v40, v212, -v183
	v_fma_f32 v41, v41, v212, v234
	v_mul_f32_e32 v183, v43, v215
	v_mul_f32_e32 v234, v42, v215
	v_fma_f32 v42, v42, v214, -v183
	v_fma_f32 v43, v43, v214, v234
	s_mov_b64 exec, s[96:97]
	v_cvt_pk_bf16_f32 v184, v44, v45
	v_cvt_pk_bf16_f32 v185, v46, v47
	v_cvt_pk_bf16_f32 v186, v40, v41
	v_cvt_pk_bf16_f32 v187, v42, v43
	global_store_dwordx4 v181, v[184:187], s[62:63]
	s_mov_b64 exec, s[68:69]
	v_mul_f32_e32 v183, v37, v209
	v_mul_f32_e32 v234, v36, v209
	v_fma_f32 v36, v36, v208, -v183
	v_fma_f32 v37, v37, v208, v234
	v_mul_f32_e32 v183, v39, v211
	v_mul_f32_e32 v234, v38, v211
	v_fma_f32 v38, v38, v210, -v183
	v_fma_f32 v39, v39, v210, v234
	v_mul_f32_e32 v183, v33, v213
	v_mul_f32_e32 v234, v32, v213
	v_fma_f32 v32, v32, v212, -v183
	v_fma_f32 v33, v33, v212, v234
	v_mul_f32_e32 v183, v35, v215
	v_mul_f32_e32 v234, v34, v215
	v_fma_f32 v34, v34, v214, -v183
	v_fma_f32 v35, v35, v214, v234
	s_mov_b64 exec, s[96:97]
	v_cvt_pk_bf16_f32 v188, v36, v37
	v_cvt_pk_bf16_f32 v189, v38, v39
	v_cvt_pk_bf16_f32 v190, v32, v33
	v_cvt_pk_bf16_f32 v191, v34, v35
	global_store_dwordx4 v181, v[188:191], s[64:65]
	s_add_u32 s62, s66, 0xa000
	s_addc_u32 s63, s67, 0
	s_add_u32 s64, s66, 0x8a000
	s_addc_u32 s65, s67, 0
	s_waitcnt vmcnt(8)
	s_mov_b64 exec, s[68:69]
	v_mul_f32_e32 v183, v29, v217
	v_mul_f32_e32 v234, v28, v217
	v_fma_f32 v28, v28, v216, -v183
	v_fma_f32 v29, v29, v216, v234
	v_mul_f32_e32 v183, v31, v219
	v_mul_f32_e32 v234, v30, v219
	v_fma_f32 v30, v30, v218, -v183
	v_fma_f32 v31, v31, v218, v234
	v_mul_f32_e32 v183, v25, v221
	v_mul_f32_e32 v234, v24, v221
	v_fma_f32 v24, v24, v220, -v183
	v_fma_f32 v25, v25, v220, v234
	v_mul_f32_e32 v183, v27, v223
	v_mul_f32_e32 v234, v26, v223
	v_fma_f32 v26, v26, v222, -v183
	v_fma_f32 v27, v27, v222, v234
	s_mov_b64 exec, s[96:97]
	v_cvt_pk_bf16_f32 v184, v28, v29
	v_cvt_pk_bf16_f32 v185, v30, v31
	v_cvt_pk_bf16_f32 v186, v24, v25
	v_cvt_pk_bf16_f32 v187, v26, v27
	global_store_dwordx4 v181, v[184:187], s[62:63]
	s_mov_b64 exec, s[68:69]
	v_mul_f32_e32 v183, v21, v217
	v_mul_f32_e32 v234, v20, v217
	v_fma_f32 v20, v20, v216, -v183
	v_fma_f32 v21, v21, v216, v234
	v_mul_f32_e32 v183, v23, v219
	v_mul_f32_e32 v234, v22, v219
	v_fma_f32 v22, v22, v218, -v183
	v_fma_f32 v23, v23, v218, v234
	v_mul_f32_e32 v183, v17, v221
	v_mul_f32_e32 v234, v16, v221
	v_fma_f32 v16, v16, v220, -v183
	v_fma_f32 v17, v17, v220, v234
	v_mul_f32_e32 v183, v19, v223
	v_mul_f32_e32 v234, v18, v223
	v_fma_f32 v18, v18, v222, -v183
	v_fma_f32 v19, v19, v222, v234
	s_mov_b64 exec, s[96:97]
	v_cvt_pk_bf16_f32 v188, v20, v21
	v_cvt_pk_bf16_f32 v189, v22, v23
	v_cvt_pk_bf16_f32 v190, v16, v17
	v_cvt_pk_bf16_f32 v191, v18, v19
	global_store_dwordx4 v181, v[188:191], s[64:65]
	s_add_u32 s62, s66, 0xb000
	s_addc_u32 s63, s67, 0
	s_add_u32 s64, s66, 0x8b000
	s_addc_u32 s65, s67, 0
	s_waitcnt vmcnt(6)
	s_mov_b64 exec, s[68:69]
	v_mul_f32_e32 v183, v13, v227
	v_mul_f32_e32 v234, v12, v227
	v_fma_f32 v12, v12, v226, -v183
	v_fma_f32 v13, v13, v226, v234
	v_mul_f32_e32 v183, v15, v229
	v_mul_f32_e32 v234, v14, v229
	v_fma_f32 v14, v14, v228, -v183
	v_fma_f32 v15, v15, v228, v234
	v_mul_f32_e32 v183, v9, v231
	v_mul_f32_e32 v234, v8, v231
	v_fma_f32 v8, v8, v230, -v183
	v_fma_f32 v9, v9, v230, v234
	v_mul_f32_e32 v183, v11, v233
	v_mul_f32_e32 v234, v10, v233
	v_fma_f32 v10, v10, v232, -v183
	v_fma_f32 v11, v11, v232, v234
	s_mov_b64 exec, s[96:97]
	v_cvt_pk_bf16_f32 v184, v12, v13
	v_cvt_pk_bf16_f32 v185, v14, v15
	v_cvt_pk_bf16_f32 v186, v8, v9
	v_cvt_pk_bf16_f32 v187, v10, v11
	global_store_dwordx4 v181, v[184:187], s[62:63]
	s_mov_b64 exec, s[68:69]
	v_mul_f32_e32 v183, v5, v227
	v_mul_f32_e32 v234, v4, v227
	v_fma_f32 v4, v4, v226, -v183
	v_fma_f32 v5, v5, v226, v234
	v_mul_f32_e32 v183, v7, v229
	v_mul_f32_e32 v234, v6, v229
	v_fma_f32 v6, v6, v228, -v183
	v_fma_f32 v7, v7, v228, v234
	v_mul_f32_e32 v183, v1, v231
	v_mul_f32_e32 v234, v0, v231
	v_fma_f32 v0, v0, v230, -v183
	v_fma_f32 v1, v1, v230, v234
	v_mul_f32_e32 v183, v3, v233
	v_mul_f32_e32 v234, v2, v233
	v_fma_f32 v2, v2, v232, -v183
	v_fma_f32 v3, v3, v232, v234
	s_mov_b64 exec, s[96:97]
	v_cvt_pk_bf16_f32 v188, v4, v5
	v_cvt_pk_bf16_f32 v189, v6, v7
	v_cvt_pk_bf16_f32 v190, v0, v1
	v_cvt_pk_bf16_f32 v191, v2, v3
	global_store_dwordx4 v181, v[188:191], s[64:65]
	s_branch .Lep_fast_done
.Lep_kind4n:
	v_and_b32_e32 v181, 0x7ff, v180
	v_lshlrev_b32_e32 v181, 8, v181
	v_lshl_add_u32 v181, v146, 1, v181
	s_lshr_b32 s61, s60, 3
	s_add_i32 s61, s61, 8
	s_lshl_b32 s61, s61, 3
	s_and_b32 s95, s16, 3
	s_lshl_b32 s95, s95, 1
	s_add_i32 s61, s61, s95
	s_lshl_b32 s61, s61, 19
	s_add_u32 s66, s14, s61
	s_addc_u32 s67, s15, 0
	s_add_u32 s62, s66, 0x0
	s_addc_u32 s63, s67, 0
	s_add_u32 s64, s66, 0x80000
	s_addc_u32 s65, s67, 0
	v_cvt_pk_bf16_f32 v184, v124, v125
	v_cvt_pk_bf16_f32 v185, v126, v127
	v_cvt_pk_bf16_f32 v186, v120, v121
	v_cvt_pk_bf16_f32 v187, v122, v123
	global_store_dwordx4 v181, v[184:187], s[62:63]
	v_cvt_pk_bf16_f32 v188, v116, v117
	v_cvt_pk_bf16_f32 v189, v118, v119
	v_cvt_pk_bf16_f32 v190, v112, v113
	v_cvt_pk_bf16_f32 v191, v114, v115
	global_store_dwordx4 v181, v[188:191], s[64:65]
	s_add_u32 s62, s66, 0x1000
	s_addc_u32 s63, s67, 0
	s_add_u32 s64, s66, 0x81000
	s_addc_u32 s65, s67, 0
	v_cvt_pk_bf16_f32 v184, v108, v109
	v_cvt_pk_bf16_f32 v185, v110, v111
	v_cvt_pk_bf16_f32 v186, v104, v105
	v_cvt_pk_bf16_f32 v187, v106, v107
	global_store_dwordx4 v181, v[184:187], s[62:63]
	v_cvt_pk_bf16_f32 v188, v100, v101
	v_cvt_pk_bf16_f32 v189, v102, v103
	v_cvt_pk_bf16_f32 v190, v96, v97
	v_cvt_pk_bf16_f32 v191, v98, v99
	global_store_dwordx4 v181, v[188:191], s[64:65]
	s_add_u32 s62, s66, 0x2000
	s_addc_u32 s63, s67, 0
	s_add_u32 s64, s66, 0x82000
	s_addc_u32 s65, s67, 0
	v_cvt_pk_bf16_f32 v184, v92, v93
	v_cvt_pk_bf16_f32 v185, v94, v95
	v_cvt_pk_bf16_f32 v186, v88, v89
	v_cvt_pk_bf16_f32 v187, v90, v91
	global_store_dwordx4 v181, v[184:187], s[62:63]
	v_cvt_pk_bf16_f32 v188, v84, v85
	v_cvt_pk_bf16_f32 v189, v86, v87
	v_cvt_pk_bf16_f32 v190, v80, v81
	v_cvt_pk_bf16_f32 v191, v82, v83
	global_store_dwordx4 v181, v[188:191], s[64:65]
	s_add_u32 s62, s66, 0x3000
	s_addc_u32 s63, s67, 0
	s_add_u32 s64, s66, 0x83000
	s_addc_u32 s65, s67, 0
	v_cvt_pk_bf16_f32 v184, v76, v77
	v_cvt_pk_bf16_f32 v185, v78, v79
	v_cvt_pk_bf16_f32 v186, v72, v73
	v_cvt_pk_bf16_f32 v187, v74, v75
	global_store_dwordx4 v181, v[184:187], s[62:63]
	v_cvt_pk_bf16_f32 v188, v68, v69
	v_cvt_pk_bf16_f32 v189, v70, v71
	v_cvt_pk_bf16_f32 v190, v64, v65
	v_cvt_pk_bf16_f32 v191, v66, v67
	global_store_dwordx4 v181, v[188:191], s[64:65]
	s_add_u32 s62, s66, 0x8000
	s_addc_u32 s63, s67, 0
	s_add_u32 s64, s66, 0x88000
	s_addc_u32 s65, s67, 0
	v_cvt_pk_bf16_f32 v184, v60, v61
	v_cvt_pk_bf16_f32 v185, v62, v63
	v_cvt_pk_bf16_f32 v186, v56, v57
	v_cvt_pk_bf16_f32 v187, v58, v59
	global_store_dwordx4 v181, v[184:187], s[62:63]
	v_cvt_pk_bf16_f32 v188, v52, v53
	v_cvt_pk_bf16_f32 v189, v54, v55
	v_cvt_pk_bf16_f32 v190, v48, v49
	v_cvt_pk_bf16_f32 v191, v50, v51
	global_store_dwordx4 v181, v[188:191], s[64:65]
	s_add_u32 s62, s66, 0x9000
	s_addc_u32 s63, s67, 0
	s_add_u32 s64, s66, 0x89000
	s_addc_u32 s65, s67, 0
	v_cvt_pk_bf16_f32 v184, v44, v45
	v_cvt_pk_bf16_f32 v185, v46, v47
	v_cvt_pk_bf16_f32 v186, v40, v41
	v_cvt_pk_bf16_f32 v187, v42, v43
	global_store_dwordx4 v181, v[184:187], s[62:63]
	v_cvt_pk_bf16_f32 v188, v36, v37
	v_cvt_pk_bf16_f32 v189, v38, v39
	v_cvt_pk_bf16_f32 v190, v32, v33
	v_cvt_pk_bf16_f32 v191, v34, v35
	global_store_dwordx4 v181, v[188:191], s[64:65]
	s_add_u32 s62, s66, 0xa000
	s_addc_u32 s63, s67, 0
	s_add_u32 s64, s66, 0x8a000
	s_addc_u32 s65, s67, 0
	v_cvt_pk_bf16_f32 v184, v28, v29
	v_cvt_pk_bf16_f32 v185, v30, v31
	v_cvt_pk_bf16_f32 v186, v24, v25
	v_cvt_pk_bf16_f32 v187, v26, v27
	global_store_dwordx4 v181, v[184:187], s[62:63]
	v_cvt_pk_bf16_f32 v188, v20, v21
	v_cvt_pk_bf16_f32 v189, v22, v23
	v_cvt_pk_bf16_f32 v190, v16, v17
	v_cvt_pk_bf16_f32 v191, v18, v19
	global_store_dwordx4 v181, v[188:191], s[64:65]
	s_add_u32 s62, s66, 0xb000
	s_addc_u32 s63, s67, 0
	s_add_u32 s64, s66, 0x8b000
	s_addc_u32 s65, s67, 0
	v_cvt_pk_bf16_f32 v184, v12, v13
	v_cvt_pk_bf16_f32 v185, v14, v15
	v_cvt_pk_bf16_f32 v186, v8, v9
	v_cvt_pk_bf16_f32 v187, v10, v11
	global_store_dwordx4 v181, v[184:187], s[62:63]
	v_cvt_pk_bf16_f32 v188, v4, v5
	v_cvt_pk_bf16_f32 v189, v6, v7
	v_cvt_pk_bf16_f32 v190, v0, v1
	v_cvt_pk_bf16_f32 v191, v2, v3
	global_store_dwordx4 v181, v[188:191], s[64:65]
	s_branch .Lep_fast_done
.Lep_fast_done:
	s_andn2_b64 vcc, exec, s[4:5]
	s_mov_b64 s[4:5], -1
	s_branch .Lep_done
.Lep_generic:
	s_cmp_eq_u32 s51, 4
	s_cselect_b64 s[64:65], -1, 0
	s_and_b64 s[62:63], s[64:65], exec
	s_cselect_b32 s55, 8, 0
	s_cmp_lt_i32 s51, 4
	s_cbranch_scc1 .LBB0_270
	s_cmp_eq_u32 s51, 4
	s_cselect_b64 s[66:67], -1, 0
	s_cbranch_execz .LBB0_271
	s_branch .LBB0_272

.Lep_done:
	s_cbranch_vccnz .LBB0_261
	s_andn2_b64 vcc, exec, s[38:39]
	s_cbranch_vccnz .LBB0_260
	s_barrier
	s_branch .LBB0_260
